# K-loops: priority swapped (loader segment prio 1, MFMA segment prio 0)
# baseline (speedup 1.0000x reference)
.LBB0_100:
	ds_read_b128 v[146:149], v143
	ds_read_b128 v[150:153], v143 offset:1024
	ds_read_b128 v[154:157], v143 offset:2048
	ds_read_b128 v[158:161], v143 offset:3072
	s_add_u32 s20, s18, 0xfffc0080
	s_addc_u32 s21, s19, -1
	s_cmp_eq_u32 s62, 12
	s_cselect_b32 s23, s11, s21
	s_cselect_b32 s22, s50, s20
	s_cselect_b32 s21, s13, s61
	s_cselect_b32 s20, s51, s60
	v_lshl_add_u64 v[194:195], s[18:19], 0, v[132:133]
	s_add_i32 m0, s9, 0xc000
	ds_read_b128 v[162:165], v144
	ds_read_b128 v[166:169], v144 offset:1024
	ds_read_b128 v[170:173], v144 offset:2048
	ds_read_b128 v[174:177], v144 offset:3072
	ds_read_b128 v[178:181], v144 offset:4096
	ds_read_b128 v[182:185], v144 offset:5120
	ds_read_b128 v[186:189], v144 offset:6144
	ds_read_b128 v[190:193], v144 offset:7168
	global_load_lds_dwordx4 v[194:195], off
	v_lshl_add_u64 v[194:195], s[18:19], 0, v[134:135]
	s_add_i32 m0, s9, 0xe000
	s_nop 0
	global_load_lds_dwordx4 v[194:195], off
	s_waitcnt lgkmcnt(8)
	s_barrier
	s_waitcnt lgkmcnt(0)
	s_setprio 0
	s_waitcnt lgkmcnt(0)
	v_mfma_f32_16x16x32_bf16 v[124:127], v[146:149], v[162:165], v[124:127]
	v_mfma_f32_16x16x32_bf16 v[120:123], v[154:157], v[162:165], v[120:123]
	v_mfma_f32_16x16x32_bf16 v[116:119], v[146:149], v[170:173], v[116:119]
	v_mfma_f32_16x16x32_bf16 v[108:111], v[154:157], v[170:173], v[108:111]
	v_mfma_f32_16x16x32_bf16 v[100:103], v[146:149], v[178:181], v[100:103]
	v_mfma_f32_16x16x32_bf16 v[92:95], v[154:157], v[178:181], v[92:95]
	v_mfma_f32_16x16x32_bf16 v[84:87], v[146:149], v[186:189], v[84:87]
	v_mfma_f32_16x16x32_bf16 v[76:79], v[154:157], v[186:189], v[76:79]
	v_mfma_f32_16x16x32_bf16 v[124:127], v[150:153], v[166:169], v[124:127]
	v_mfma_f32_16x16x32_bf16 v[120:123], v[158:161], v[166:169], v[120:123]
	v_mfma_f32_16x16x32_bf16 v[116:119], v[150:153], v[174:177], v[116:119]
	v_mfma_f32_16x16x32_bf16 v[108:111], v[158:161], v[174:177], v[108:111]
	v_mfma_f32_16x16x32_bf16 v[100:103], v[150:153], v[182:185], v[100:103]
	v_mfma_f32_16x16x32_bf16 v[92:95], v[158:161], v[182:185], v[92:95]
	v_mfma_f32_16x16x32_bf16 v[84:87], v[150:153], v[190:193], v[84:87]
	v_mfma_f32_16x16x32_bf16 v[76:79], v[158:161], v[190:193], v[76:79]
	s_setprio 1
	s_barrier
	s_add_i32 s63, s47, s35
	v_lshl_add_u64 v[210:211], s[20:21], 0, v[128:129]
	s_mov_b32 m0, s63
	ds_read_b128 v[194:197], v145
	ds_read_b128 v[198:201], v145 offset:1024
	ds_read_b128 v[202:205], v145 offset:2048
	ds_read_b128 v[206:209], v145 offset:3072
	global_load_lds_dwordx4 v[210:211], off
	v_lshl_add_u64 v[212:213], s[20:21], 0, v[130:131]
	s_add_i32 m0, s63, 0x2000
	s_nop 0
	global_load_lds_dwordx4 v[212:213], off
	s_barrier
	s_waitcnt lgkmcnt(0)
	s_setprio 0
	s_waitcnt lgkmcnt(0)
	v_mfma_f32_16x16x32_bf16 v[112:115], v[194:197], v[162:165], v[112:115]
	v_mfma_f32_16x16x32_bf16 v[104:107], v[202:205], v[162:165], v[104:107]
	v_mfma_f32_16x16x32_bf16 v[96:99], v[194:197], v[170:173], v[96:99]
	v_mfma_f32_16x16x32_bf16 v[88:91], v[202:205], v[170:173], v[88:91]
	v_mfma_f32_16x16x32_bf16 v[80:83], v[194:197], v[178:181], v[80:83]
	v_mfma_f32_16x16x32_bf16 v[72:75], v[202:205], v[178:181], v[72:75]
	v_mfma_f32_16x16x32_bf16 v[68:71], v[194:197], v[186:189], v[68:71]
	v_mfma_f32_16x16x32_bf16 v[64:67], v[202:205], v[186:189], v[64:67]
	v_mfma_f32_16x16x32_bf16 v[112:115], v[198:201], v[166:169], v[112:115]
	v_mfma_f32_16x16x32_bf16 v[104:107], v[206:209], v[166:169], v[104:107]
	v_mfma_f32_16x16x32_bf16 v[96:99], v[198:201], v[174:177], v[96:99]
	v_mfma_f32_16x16x32_bf16 v[88:91], v[206:209], v[174:177], v[88:91]
	v_mfma_f32_16x16x32_bf16 v[80:83], v[198:201], v[182:185], v[80:83]
	v_mfma_f32_16x16x32_bf16 v[72:75], v[206:209], v[182:185], v[72:75]
	v_mfma_f32_16x16x32_bf16 v[68:71], v[198:201], v[190:193], v[68:71]
	v_mfma_f32_16x16x32_bf16 v[64:67], v[206:209], v[190:193], v[64:67]
	s_setprio 1
	s_mov_b32 m0, s9
	v_lshl_add_u64 v[214:215], s[22:23], 0, v[128:129]
	s_barrier
	ds_read_b128 v[162:165], v144 offset:16384
	ds_read_b128 v[166:169], v144 offset:17408
	ds_read_b128 v[170:173], v144 offset:18432
	ds_read_b128 v[174:177], v144 offset:19456
	ds_read_b128 v[178:181], v144 offset:20480
	ds_read_b128 v[182:185], v144 offset:21504
	ds_read_b128 v[186:189], v144 offset:22528
	ds_read_b128 v[190:193], v144 offset:23552
	global_load_lds_dwordx4 v[214:215], off
	v_lshl_add_u64 v[216:217], s[22:23], 0, v[130:131]
	s_mov_b32 m0, s36
	s_nop 0
	global_load_lds_dwordx4 v[216:217], off
	s_barrier
	s_waitcnt lgkmcnt(0)
	s_setprio 0
	s_waitcnt lgkmcnt(0)
	v_mfma_f32_16x16x32_bf16 v[60:63], v[146:149], v[162:165], v[60:63]
	v_mfma_f32_16x16x32_bf16 v[56:59], v[154:157], v[162:165], v[56:59]
	v_mfma_f32_16x16x32_bf16 v[52:55], v[146:149], v[170:173], v[52:55]
	v_mfma_f32_16x16x32_bf16 v[48:51], v[154:157], v[170:173], v[48:51]
	v_mfma_f32_16x16x32_bf16 v[36:39], v[146:149], v[178:181], v[36:39]
	v_mfma_f32_16x16x32_bf16 v[32:35], v[154:157], v[178:181], v[32:35]
	v_mfma_f32_16x16x32_bf16 v[20:23], v[146:149], v[186:189], v[20:23]
	v_mfma_f32_16x16x32_bf16 v[16:19], v[154:157], v[186:189], v[16:19]
	v_mfma_f32_16x16x32_bf16 v[60:63], v[150:153], v[166:169], v[60:63]
	v_mfma_f32_16x16x32_bf16 v[56:59], v[158:161], v[166:169], v[56:59]
	v_mfma_f32_16x16x32_bf16 v[52:55], v[150:153], v[174:177], v[52:55]
	v_mfma_f32_16x16x32_bf16 v[48:51], v[158:161], v[174:177], v[48:51]
	v_mfma_f32_16x16x32_bf16 v[36:39], v[150:153], v[182:185], v[36:39]
	v_mfma_f32_16x16x32_bf16 v[32:35], v[158:161], v[182:185], v[32:35]
	v_mfma_f32_16x16x32_bf16 v[20:23], v[150:153], v[190:193], v[20:23]
	v_mfma_f32_16x16x32_bf16 v[16:19], v[158:161], v[190:193], v[16:19]
	s_setprio 1
	s_barrier
	s_add_u32 s68, s20, 0x40000
	s_addc_u32 s69, s21, 0
	s_add_i32 s63, s48, s35
	v_lshl_add_u64 v[146:147], s[68:69], 0, v[128:129]
	s_mov_b32 m0, s63
	s_nop 0
	global_load_lds_dwordx4 v[146:147], off
	v_lshl_add_u64 v[146:147], s[68:69], 0, v[130:131]
	s_add_i32 m0, s63, 0x2000
	s_nop 0
	global_load_lds_dwordx4 v[146:147], off
	s_waitcnt vmcnt(6)
	s_barrier
	s_setprio 0
	v_mfma_f32_16x16x32_bf16 v[44:47], v[194:197], v[162:165], v[44:47]
	v_mfma_f32_16x16x32_bf16 v[40:43], v[202:205], v[162:165], v[40:43]
	v_mfma_f32_16x16x32_bf16 v[28:31], v[194:197], v[170:173], v[28:31]
	v_mfma_f32_16x16x32_bf16 v[24:27], v[202:205], v[170:173], v[24:27]
	v_mfma_f32_16x16x32_bf16 v[12:15], v[194:197], v[178:181], v[12:15]
	v_mfma_f32_16x16x32_bf16 v[8:11], v[202:205], v[178:181], v[8:11]
	v_mfma_f32_16x16x32_bf16 v[4:7], v[194:197], v[186:189], v[4:7]
	v_mfma_f32_16x16x32_bf16 v[0:3], v[202:205], v[186:189], v[0:3]
	v_mfma_f32_16x16x32_bf16 v[44:47], v[198:201], v[166:169], v[44:47]
	v_mfma_f32_16x16x32_bf16 v[40:43], v[206:209], v[166:169], v[40:43]
	v_mfma_f32_16x16x32_bf16 v[28:31], v[198:201], v[174:177], v[28:31]
	v_mfma_f32_16x16x32_bf16 v[24:27], v[206:209], v[174:177], v[24:27]
	v_mfma_f32_16x16x32_bf16 v[12:15], v[198:201], v[182:185], v[12:15]
	v_mfma_f32_16x16x32_bf16 v[8:11], v[206:209], v[182:185], v[8:11]
	v_mfma_f32_16x16x32_bf16 v[4:7], v[198:201], v[190:193], v[4:7]
	v_mfma_f32_16x16x32_bf16 v[0:3], v[206:209], v[190:193], v[0:3]
	s_setprio 1
	s_add_i32 s63, 0, 0x18000
	v_add_u32_e32 v158, s63, v141
	s_barrier
	ds_read_b128 v[146:149], v158
	ds_read_b128 v[150:153], v158 offset:1024
	ds_read_b128 v[154:157], v158 offset:2048
	ds_read_b128 v[158:161], v158 offset:3072
	s_add_u32 s22, s22, 0x40000
	s_addc_u32 s23, s23, 0
	s_mov_b32 m0, s37
	v_lshl_add_u64 v[194:195], s[22:23], 0, v[128:129]
	ds_read_b128 v[162:165], v144 offset:32768
	ds_read_b128 v[166:169], v144 offset:33792
	ds_read_b128 v[170:173], v144 offset:34816
	ds_read_b128 v[174:177], v144 offset:35840
	ds_read_b128 v[178:181], v144 offset:36864
	ds_read_b128 v[182:185], v144 offset:37888
	ds_read_b128 v[186:189], v144 offset:38912
	ds_read_b128 v[190:193], v144 offset:39936
	global_load_lds_dwordx4 v[194:195], off
	v_lshl_add_u64 v[194:195], s[22:23], 0, v[130:131]
	s_mov_b32 m0, s38
	s_nop 0
	global_load_lds_dwordx4 v[194:195], off
	s_waitcnt lgkmcnt(8)
	s_barrier
	s_waitcnt lgkmcnt(0)
	s_setprio 0
	s_waitcnt lgkmcnt(0)
	v_mfma_f32_16x16x32_bf16 v[124:127], v[146:149], v[162:165], v[124:127]
	v_mfma_f32_16x16x32_bf16 v[120:123], v[154:157], v[162:165], v[120:123]
	v_mfma_f32_16x16x32_bf16 v[116:119], v[146:149], v[170:173], v[116:119]
	v_mfma_f32_16x16x32_bf16 v[108:111], v[154:157], v[170:173], v[108:111]
	v_mfma_f32_16x16x32_bf16 v[100:103], v[146:149], v[178:181], v[100:103]
	v_mfma_f32_16x16x32_bf16 v[92:95], v[154:157], v[178:181], v[92:95]
	v_mfma_f32_16x16x32_bf16 v[84:87], v[146:149], v[186:189], v[84:87]
	v_mfma_f32_16x16x32_bf16 v[76:79], v[154:157], v[186:189], v[76:79]
	v_mfma_f32_16x16x32_bf16 v[124:127], v[150:153], v[166:169], v[124:127]
	v_mfma_f32_16x16x32_bf16 v[120:123], v[158:161], v[166:169], v[120:123]
	v_mfma_f32_16x16x32_bf16 v[116:119], v[150:153], v[174:177], v[116:119]
	v_mfma_f32_16x16x32_bf16 v[108:111], v[158:161], v[174:177], v[108:111]
	v_mfma_f32_16x16x32_bf16 v[100:103], v[150:153], v[182:185], v[100:103]
	v_mfma_f32_16x16x32_bf16 v[92:95], v[158:161], v[182:185], v[92:95]
	v_mfma_f32_16x16x32_bf16 v[84:87], v[150:153], v[190:193], v[84:87]
	v_mfma_f32_16x16x32_bf16 v[76:79], v[158:161], v[190:193], v[76:79]
	s_setprio 1
	s_barrier
	s_add_i32 s22, 0, 0x1c000
	s_add_i32 s23, s63, s35
	v_add_u32_e32 v206, s22, v141
	v_lshl_add_u64 v[210:211], v[210:211], 0, s[6:7]
	s_mov_b32 m0, s23
	ds_read_b128 v[194:197], v206
	ds_read_b128 v[198:201], v206 offset:1024
	ds_read_b128 v[202:205], v206 offset:2048
	ds_read_b128 v[206:209], v206 offset:3072
	global_load_lds_dwordx4 v[210:211], off
	v_lshl_add_u64 v[210:211], v[212:213], 0, s[6:7]
	s_add_i32 m0, s23, 0x2000
	s_nop 0
	global_load_lds_dwordx4 v[210:211], off
	s_barrier
	s_waitcnt lgkmcnt(0)
	s_setprio 0
	s_waitcnt lgkmcnt(0)
	v_mfma_f32_16x16x32_bf16 v[112:115], v[194:197], v[162:165], v[112:115]
	v_mfma_f32_16x16x32_bf16 v[104:107], v[202:205], v[162:165], v[104:107]
	v_mfma_f32_16x16x32_bf16 v[96:99], v[194:197], v[170:173], v[96:99]
	v_mfma_f32_16x16x32_bf16 v[88:91], v[202:205], v[170:173], v[88:91]
	v_mfma_f32_16x16x32_bf16 v[80:83], v[194:197], v[178:181], v[80:83]
	v_mfma_f32_16x16x32_bf16 v[72:75], v[202:205], v[178:181], v[72:75]
	v_mfma_f32_16x16x32_bf16 v[68:71], v[194:197], v[186:189], v[68:71]
	v_mfma_f32_16x16x32_bf16 v[64:67], v[202:205], v[186:189], v[64:67]
	v_mfma_f32_16x16x32_bf16 v[112:115], v[198:201], v[166:169], v[112:115]
	v_mfma_f32_16x16x32_bf16 v[104:107], v[206:209], v[166:169], v[104:107]
	v_mfma_f32_16x16x32_bf16 v[96:99], v[198:201], v[174:177], v[96:99]
	v_mfma_f32_16x16x32_bf16 v[88:91], v[206:209], v[174:177], v[88:91]
	v_mfma_f32_16x16x32_bf16 v[80:83], v[198:201], v[182:185], v[80:83]
	v_mfma_f32_16x16x32_bf16 v[72:75], v[206:209], v[182:185], v[72:75]
	v_mfma_f32_16x16x32_bf16 v[68:71], v[198:201], v[190:193], v[68:71]
	v_mfma_f32_16x16x32_bf16 v[64:67], v[206:209], v[190:193], v[64:67]
	s_setprio 1
	s_mov_b32 m0, s41
	v_lshl_add_u64 v[210:211], v[214:215], 0, s[6:7]
	s_barrier
	ds_read_b128 v[162:165], v144 offset:49152
	ds_read_b128 v[166:169], v144 offset:50176
	ds_read_b128 v[170:173], v144 offset:51200
	ds_read_b128 v[174:177], v144 offset:52224
	ds_read_b128 v[178:181], v144 offset:53248
	ds_read_b128 v[182:185], v144 offset:54272
	ds_read_b128 v[186:189], v144 offset:55296
	ds_read_b128 v[190:193], v144 offset:56320
	global_load_lds_dwordx4 v[210:211], off
	v_lshl_add_u64 v[210:211], v[216:217], 0, s[6:7]
	s_mov_b32 m0, s43
	s_nop 0
	global_load_lds_dwordx4 v[210:211], off
	s_barrier
	s_waitcnt lgkmcnt(0)
	s_setprio 0
	s_waitcnt lgkmcnt(0)
	v_mfma_f32_16x16x32_bf16 v[60:63], v[146:149], v[162:165], v[60:63]
	v_mfma_f32_16x16x32_bf16 v[56:59], v[154:157], v[162:165], v[56:59]
	v_mfma_f32_16x16x32_bf16 v[52:55], v[146:149], v[170:173], v[52:55]
	v_mfma_f32_16x16x32_bf16 v[48:51], v[154:157], v[170:173], v[48:51]
	v_mfma_f32_16x16x32_bf16 v[36:39], v[146:149], v[178:181], v[36:39]
	v_mfma_f32_16x16x32_bf16 v[32:35], v[154:157], v[178:181], v[32:35]
	v_mfma_f32_16x16x32_bf16 v[20:23], v[146:149], v[186:189], v[20:23]
	v_mfma_f32_16x16x32_bf16 v[16:19], v[154:157], v[186:189], v[16:19]
	v_mfma_f32_16x16x32_bf16 v[60:63], v[150:153], v[166:169], v[60:63]
	v_mfma_f32_16x16x32_bf16 v[56:59], v[158:161], v[166:169], v[56:59]
	v_mfma_f32_16x16x32_bf16 v[52:55], v[150:153], v[174:177], v[52:55]
	v_mfma_f32_16x16x32_bf16 v[48:51], v[158:161], v[174:177], v[48:51]
	v_mfma_f32_16x16x32_bf16 v[36:39], v[150:153], v[182:185], v[36:39]
	v_mfma_f32_16x16x32_bf16 v[32:35], v[158:161], v[182:185], v[32:35]
	v_mfma_f32_16x16x32_bf16 v[20:23], v[150:153], v[190:193], v[20:23]
	v_mfma_f32_16x16x32_bf16 v[16:19], v[158:161], v[190:193], v[16:19]
	s_setprio 1
	s_barrier
	s_add_u32 s20, s20, 0x40080
	s_addc_u32 s21, s21, 0
	s_add_i32 s22, s22, s35
	v_lshl_add_u64 v[146:147], s[20:21], 0, v[128:129]
	s_mov_b32 m0, s22
	s_nop 0
	global_load_lds_dwordx4 v[146:147], off
	v_lshl_add_u64 v[146:147], s[20:21], 0, v[130:131]
	s_add_i32 m0, s22, 0x2000
	s_nop 0
	global_load_lds_dwordx4 v[146:147], off
	s_waitcnt vmcnt(6)
	s_barrier
	s_setprio 0
	v_mfma_f32_16x16x32_bf16 v[44:47], v[194:197], v[162:165], v[44:47]
	v_mfma_f32_16x16x32_bf16 v[40:43], v[202:205], v[162:165], v[40:43]
	v_mfma_f32_16x16x32_bf16 v[28:31], v[194:197], v[170:173], v[28:31]
	v_mfma_f32_16x16x32_bf16 v[24:27], v[202:205], v[170:173], v[24:27]
	v_mfma_f32_16x16x32_bf16 v[12:15], v[194:197], v[178:181], v[12:15]
	v_mfma_f32_16x16x32_bf16 v[8:11], v[202:205], v[178:181], v[8:11]
	v_mfma_f32_16x16x32_bf16 v[4:7], v[194:197], v[186:189], v[4:7]
	v_mfma_f32_16x16x32_bf16 v[0:3], v[202:205], v[186:189], v[0:3]
	v_mfma_f32_16x16x32_bf16 v[44:47], v[198:201], v[166:169], v[44:47]
	v_mfma_f32_16x16x32_bf16 v[40:43], v[206:209], v[166:169], v[40:43]
	v_mfma_f32_16x16x32_bf16 v[28:31], v[198:201], v[174:177], v[28:31]
	v_mfma_f32_16x16x32_bf16 v[24:27], v[206:209], v[174:177], v[24:27]
	v_mfma_f32_16x16x32_bf16 v[12:15], v[198:201], v[182:185], v[12:15]
	v_mfma_f32_16x16x32_bf16 v[8:11], v[206:209], v[182:185], v[8:11]
	v_mfma_f32_16x16x32_bf16 v[4:7], v[198:201], v[190:193], v[4:7]
	v_mfma_f32_16x16x32_bf16 v[0:3], v[206:209], v[190:193], v[0:3]
	s_setprio 1
	s_add_i32 s62, s62, 2
	s_add_u32 s18, s18, 0x100
	s_addc_u32 s19, s19, 0
	s_add_u32 s60, s60, 0x100
	s_addc_u32 s61, s61, 0
	s_cmp_gt_u32 s62, 13
	s_barrier
	s_cbranch_scc0 .LBB0_100
	v_lshl_add_u32 v148, s8, 8, v140
	v_lshl_or_b32 v146, s49, 8, v142
	v_ashrrev_i32_e32 v149, 31, v148
	v_cvt_pk_bf16_f32 v112, v112, v113
	v_cvt_pk_bf16_f32 v113, v114, v115
	v_cvt_pk_bf16_f32 v114, v104, v105
	v_or_b32_e32 v104, 16, v148
	v_ashrrev_i32_e32 v147, 31, v146
	v_lshlrev_b64 v[150:151], 11, v[148:149]
	v_ashrrev_i32_e32 v105, 31, v104
	v_cvt_pk_bf16_f32 v96, v96, v97
	v_cvt_pk_bf16_f32 v97, v98, v99
	v_cvt_pk_bf16_f32 v98, v88, v89
	v_or_b32_e32 v88, 32, v148
	v_lshl_add_u64 v[150:151], s[2:3], 0, v[150:151]
	v_lshlrev_b64 v[146:147], 1, v[146:147]
	v_lshlrev_b64 v[104:105], 11, v[104:105]
	v_ashrrev_i32_e32 v89, 31, v88
	v_cvt_pk_bf16_f32 v80, v80, v81
	v_cvt_pk_bf16_f32 v81, v82, v83
	v_cvt_pk_bf16_f32 v82, v72, v73
	v_or_b32_e32 v72, 48, v148
	v_cvt_pk_bf16_f32 v68, v68, v69
	v_cvt_pk_bf16_f32 v69, v70, v71
	v_cvt_pk_bf16_f32 v70, v64, v65
	v_add_u32_e32 v64, 0x80, v148
	v_lshl_add_u64 v[150:151], v[150:151], 0, v[146:147]
	v_cvt_pk_bf16_f32 v124, v124, v125
	v_cvt_pk_bf16_f32 v125, v126, v127
	v_cvt_pk_bf16_f32 v126, v120, v121
	v_cvt_pk_bf16_f32 v127, v122, v123
	v_lshl_add_u64 v[104:105], s[2:3], 0, v[104:105]
	v_lshlrev_b64 v[88:89], 11, v[88:89]
	v_ashrrev_i32_e32 v73, 31, v72
	v_ashrrev_i32_e32 v65, 31, v64
	v_cvt_pk_bf16_f32 v44, v44, v45
	v_cvt_pk_bf16_f32 v45, v46, v47
	v_cvt_pk_bf16_f32 v46, v40, v41
	v_add_u32_e32 v40, 0x90, v148
	v_cvt_pk_bf16_f32 v115, v106, v107
	global_store_dwordx4 v[150:151], v[124:127], off
	global_store_dwordx4 v[150:151], v[112:115], off offset:64
	v_cvt_pk_bf16_f32 v106, v108, v109
	v_cvt_pk_bf16_f32 v107, v110, v111
	v_lshl_add_u64 v[112:113], v[104:105], 0, v[146:147]
	v_cvt_pk_bf16_f32 v104, v116, v117
	v_cvt_pk_bf16_f32 v105, v118, v119
	v_lshl_add_u64 v[88:89], s[2:3], 0, v[88:89]
	v_lshlrev_b64 v[72:73], 11, v[72:73]
	v_lshlrev_b64 v[64:65], 11, v[64:65]
	v_ashrrev_i32_e32 v41, 31, v40
	v_cvt_pk_bf16_f32 v28, v28, v29
	v_cvt_pk_bf16_f32 v29, v30, v31
	v_cvt_pk_bf16_f32 v30, v24, v25
	v_add_u32_e32 v24, 0xa0, v148
	v_cvt_pk_bf16_f32 v99, v90, v91
	global_store_dwordx4 v[112:113], v[104:107], off
	global_store_dwordx4 v[112:113], v[96:99], off offset:64
	v_cvt_pk_bf16_f32 v90, v92, v93
	v_cvt_pk_bf16_f32 v91, v94, v95
	v_lshl_add_u64 v[96:97], v[88:89], 0, v[146:147]
	v_cvt_pk_bf16_f32 v88, v100, v101
	v_cvt_pk_bf16_f32 v89, v102, v103
	v_lshl_add_u64 v[72:73], s[2:3], 0, v[72:73]
	v_lshl_add_u64 v[64:65], s[2:3], 0, v[64:65]
	v_lshlrev_b64 v[40:41], 11, v[40:41]
	v_ashrrev_i32_e32 v25, 31, v24
	v_cvt_pk_bf16_f32 v12, v12, v13
	v_cvt_pk_bf16_f32 v13, v14, v15
	v_cvt_pk_bf16_f32 v14, v8, v9
	v_add_u32_e32 v8, 0xb0, v148
	v_cvt_pk_bf16_f32 v83, v74, v75
	global_store_dwordx4 v[96:97], v[88:91], off
	global_store_dwordx4 v[96:97], v[80:83], off offset:64
	v_cvt_pk_bf16_f32 v74, v76, v77
	v_cvt_pk_bf16_f32 v75, v78, v79
	v_lshl_add_u64 v[80:81], v[72:73], 0, v[146:147]
	v_cvt_pk_bf16_f32 v72, v84, v85
	v_cvt_pk_bf16_f32 v73, v86, v87
	v_lshl_add_u64 v[64:65], v[64:65], 0, v[146:147]
	v_cvt_pk_bf16_f32 v60, v60, v61
	v_cvt_pk_bf16_f32 v61, v62, v63
	v_cvt_pk_bf16_f32 v62, v56, v57
	v_cvt_pk_bf16_f32 v63, v58, v59
	v_lshl_add_u64 v[40:41], s[2:3], 0, v[40:41]
	v_lshlrev_b64 v[24:25], 11, v[24:25]
	v_ashrrev_i32_e32 v9, 31, v8
	v_cvt_pk_bf16_f32 v71, v66, v67
	global_store_dwordx4 v[80:81], v[72:75], off
	global_store_dwordx4 v[80:81], v[68:71], off offset:64
	v_cvt_pk_bf16_f32 v47, v42, v43
	global_store_dwordx4 v[64:65], v[60:63], off
	global_store_dwordx4 v[64:65], v[44:47], off offset:64
	v_cvt_pk_bf16_f32 v42, v48, v49
	v_cvt_pk_bf16_f32 v43, v50, v51
	v_lshl_add_u64 v[44:45], v[40:41], 0, v[146:147]
	v_cvt_pk_bf16_f32 v40, v52, v53
	v_cvt_pk_bf16_f32 v41, v54, v55
	v_lshl_add_u64 v[24:25], s[2:3], 0, v[24:25]
	v_lshlrev_b64 v[8:9], 11, v[8:9]
	v_cvt_pk_bf16_f32 v31, v26, v27
	global_store_dwordx4 v[44:45], v[40:43], off
	global_store_dwordx4 v[44:45], v[28:31], off offset:64
	v_cvt_pk_bf16_f32 v26, v32, v33
	v_cvt_pk_bf16_f32 v27, v34, v35
	v_lshl_add_u64 v[28:29], v[24:25], 0, v[146:147]
	v_cvt_pk_bf16_f32 v24, v36, v37
	v_cvt_pk_bf16_f32 v25, v38, v39
	v_lshl_add_u64 v[8:9], s[2:3], 0, v[8:9]
	v_cvt_pk_bf16_f32 v15, v10, v11
	global_store_dwordx4 v[28:29], v[24:27], off
	global_store_dwordx4 v[28:29], v[12:15], off offset:64
	v_cvt_pk_bf16_f32 v10, v16, v17
	v_cvt_pk_bf16_f32 v11, v18, v19
	v_lshl_add_u64 v[12:13], v[8:9], 0, v[146:147]
	v_cvt_pk_bf16_f32 v8, v20, v21
	v_cvt_pk_bf16_f32 v9, v22, v23
	s_and_b64 vcc, exec, s[4:5]
	s_mov_b32 s49, s12
	s_mov_b32 s8, s10
	s_mov_b64 s[20:21], s[16:17]
	s_mov_b64 s[18:19], s[14:15]
	v_cvt_pk_bf16_f32 v4, v4, v5
	v_cvt_pk_bf16_f32 v5, v6, v7
	v_cvt_pk_bf16_f32 v6, v0, v1
	v_cvt_pk_bf16_f32 v7, v2, v3
	global_store_dwordx4 v[12:13], v[8:11], off
	global_store_dwordx4 v[12:13], v[4:7], off offset:64
	s_cbranch_vccz .LBB0_93
	s_waitcnt vmcnt(0)
	s_cmpk_gt_u32 s27, 0xff
	s_cbranch_scc1 .LBB0_104
	s_barrier

.LBB0_179:
	s_add_u32 s6, s2, 0xfffc0080
	s_addc_u32 s7, s3, -1
	s_add_i32 s33, 0, 0x10000
	v_add_u32_e32 v0, s33, v155
	ds_read_b128 v[130:133], v0
	ds_read_b128 v[134:137], v0 offset:1024
	ds_read_b128 v[138:141], v0 offset:2048
	ds_read_b128 v[142:145], v0 offset:3072
	s_cmp_eq_u32 vcc_hi, 12
	s_cselect_b32 s91, s1, s7
	s_cselect_b32 s90, s22, s6
	s_cselect_b32 s63, s23, vcc_lo
	s_cselect_b32 s62, s39, s69
	v_lshl_add_u64 v[176:177], s[2:3], 0, v[150:151]
	s_add_i32 m0, s73, 0xc000
	ds_read_b128 v[156:159], v231
	ds_read_b128 v[160:163], v231 offset:1024
	ds_read_b128 v[164:167], v231 offset:2048
	ds_read_b128 v[168:171], v231 offset:3072
	ds_read_b128 v[172:175], v231 offset:4096
	ds_read_b128 v[184:187], v231 offset:5120
	ds_read_b128 v[188:191], v231 offset:6144
	ds_read_b128 v[192:195], v231 offset:7168
	global_load_lds_dwordx4 v[176:177], off
	v_lshl_add_u64 v[176:177], s[2:3], 0, v[152:153]
	s_add_i32 m0, s73, 0xe000
	s_nop 0
	global_load_lds_dwordx4 v[176:177], off
	s_waitcnt lgkmcnt(8)
	s_barrier
	s_waitcnt lgkmcnt(0)
	s_setprio 0
	s_waitcnt lgkmcnt(0)
	v_mfma_f32_16x16x32_bf16 v[126:129], v[130:133], v[156:159], v[126:129]
	v_mfma_f32_16x16x32_bf16 v[122:125], v[138:141], v[156:159], v[122:125]
	v_mfma_f32_16x16x32_bf16 v[110:113], v[130:133], v[164:167], v[110:113]
	v_mfma_f32_16x16x32_bf16 v[106:109], v[138:141], v[164:167], v[106:109]
	v_mfma_f32_16x16x32_bf16 v[94:97], v[130:133], v[172:175], v[94:97]
	v_mfma_f32_16x16x32_bf16 v[90:93], v[138:141], v[172:175], v[90:93]
	v_mfma_f32_16x16x32_bf16 v[78:81], v[130:133], v[188:191], v[78:81]
	v_mfma_f32_16x16x32_bf16 v[74:77], v[138:141], v[188:191], v[74:77]
	v_mfma_f32_16x16x32_bf16 v[126:129], v[134:137], v[160:163], v[126:129]
	v_mfma_f32_16x16x32_bf16 v[122:125], v[142:145], v[160:163], v[122:125]
	v_mfma_f32_16x16x32_bf16 v[110:113], v[134:137], v[168:171], v[110:113]
	v_mfma_f32_16x16x32_bf16 v[106:109], v[142:145], v[168:171], v[106:109]
	v_mfma_f32_16x16x32_bf16 v[94:97], v[134:137], v[184:187], v[94:97]
	v_mfma_f32_16x16x32_bf16 v[90:93], v[142:145], v[184:187], v[90:93]
	v_mfma_f32_16x16x32_bf16 v[78:81], v[134:137], v[192:195], v[78:81]
	v_mfma_f32_16x16x32_bf16 v[74:77], v[142:145], v[192:195], v[74:77]
	s_setprio 1
	s_barrier
	s_add_i32 s94, 0, 0x14000
	s_add_i32 s6, s33, s11
	v_add_u32_e32 v0, s94, v155
	v_lshl_add_u64 v[176:177], s[62:63], 0, v[146:147]
	s_mov_b32 m0, s6
	ds_read_b128 v[196:199], v0
	ds_read_b128 v[200:203], v0 offset:1024
	ds_read_b128 v[204:207], v0 offset:2048
	ds_read_b128 v[208:211], v0 offset:3072
	global_load_lds_dwordx4 v[176:177], off
	v_lshl_add_u64 v[180:181], s[62:63], 0, v[148:149]
	s_add_i32 m0, s6, 0x2000
	s_nop 0
	global_load_lds_dwordx4 v[180:181], off
	s_barrier
	s_waitcnt lgkmcnt(0)
	s_setprio 0
	s_waitcnt lgkmcnt(0)
	v_mfma_f32_16x16x32_bf16 v[118:121], v[196:199], v[156:159], v[118:121]
	v_mfma_f32_16x16x32_bf16 v[114:117], v[204:207], v[156:159], v[114:117]
	v_mfma_f32_16x16x32_bf16 v[102:105], v[196:199], v[164:167], v[102:105]
	v_mfma_f32_16x16x32_bf16 v[98:101], v[204:207], v[164:167], v[98:101]
	v_mfma_f32_16x16x32_bf16 v[86:89], v[196:199], v[172:175], v[86:89]
	v_mfma_f32_16x16x32_bf16 v[82:85], v[204:207], v[172:175], v[82:85]
	v_mfma_f32_16x16x32_bf16 v[70:73], v[196:199], v[188:191], v[70:73]
	v_mfma_f32_16x16x32_bf16 v[66:69], v[204:207], v[188:191], v[66:69]
	v_mfma_f32_16x16x32_bf16 v[118:121], v[200:203], v[160:163], v[118:121]
	v_mfma_f32_16x16x32_bf16 v[114:117], v[208:211], v[160:163], v[114:117]
	v_mfma_f32_16x16x32_bf16 v[102:105], v[200:203], v[168:171], v[102:105]
	v_mfma_f32_16x16x32_bf16 v[98:101], v[208:211], v[168:171], v[98:101]
	v_mfma_f32_16x16x32_bf16 v[86:89], v[200:203], v[184:187], v[86:89]
	v_mfma_f32_16x16x32_bf16 v[82:85], v[208:211], v[184:187], v[82:85]
	v_mfma_f32_16x16x32_bf16 v[70:73], v[200:203], v[192:195], v[70:73]
	v_mfma_f32_16x16x32_bf16 v[66:69], v[208:211], v[192:195], v[66:69]
	s_setprio 1
	s_mov_b32 m0, s73
	v_lshl_add_u64 v[212:213], s[90:91], 0, v[146:147]
	s_barrier
	ds_read_b128 v[156:159], v231 offset:16384
	ds_read_b128 v[160:163], v231 offset:17408
	ds_read_b128 v[164:167], v231 offset:18432
	ds_read_b128 v[168:171], v231 offset:19456
	ds_read_b128 v[172:175], v231 offset:20480
	ds_read_b128 v[184:187], v231 offset:21504
	ds_read_b128 v[188:191], v231 offset:22528
	ds_read_b128 v[192:195], v231 offset:23552
	global_load_lds_dwordx4 v[212:213], off
	v_lshl_add_u64 v[214:215], s[90:91], 0, v[148:149]
	s_mov_b32 m0, s14
	s_nop 0
	global_load_lds_dwordx4 v[214:215], off
	s_barrier
	s_waitcnt lgkmcnt(0)
	s_setprio 0
	s_waitcnt lgkmcnt(0)
	v_mfma_f32_16x16x32_bf16 v[62:65], v[130:133], v[156:159], v[62:65]
	v_mfma_f32_16x16x32_bf16 v[58:61], v[138:141], v[156:159], v[58:61]
	v_mfma_f32_16x16x32_bf16 v[46:49], v[130:133], v[164:167], v[46:49]
	v_mfma_f32_16x16x32_bf16 v[42:45], v[138:141], v[164:167], v[42:45]
	v_mfma_f32_16x16x32_bf16 v[30:33], v[130:133], v[172:175], v[30:33]
	v_mfma_f32_16x16x32_bf16 v[26:29], v[138:141], v[172:175], v[26:29]
	v_mfma_f32_16x16x32_bf16 v[14:17], v[130:133], v[188:191], v[14:17]
	v_mfma_f32_16x16x32_bf16 v[10:13], v[138:141], v[188:191], v[10:13]
	v_mfma_f32_16x16x32_bf16 v[62:65], v[134:137], v[160:163], v[62:65]
	v_mfma_f32_16x16x32_bf16 v[58:61], v[142:145], v[160:163], v[58:61]
	v_mfma_f32_16x16x32_bf16 v[46:49], v[134:137], v[168:171], v[46:49]
	v_mfma_f32_16x16x32_bf16 v[42:45], v[142:145], v[168:171], v[42:45]
	v_mfma_f32_16x16x32_bf16 v[30:33], v[134:137], v[184:187], v[30:33]
	v_mfma_f32_16x16x32_bf16 v[26:29], v[142:145], v[184:187], v[26:29]
	v_mfma_f32_16x16x32_bf16 v[14:17], v[134:137], v[192:195], v[14:17]
	v_mfma_f32_16x16x32_bf16 v[10:13], v[142:145], v[192:195], v[10:13]
	s_setprio 1
	s_barrier
	s_add_u32 s6, s62, 0x40000
	s_addc_u32 s7, s63, 0
	s_add_i32 s33, s94, s11
	v_lshl_add_u64 v[130:131], s[6:7], 0, v[146:147]
	s_mov_b32 m0, s33
	s_nop 0
	global_load_lds_dwordx4 v[130:131], off
	v_lshl_add_u64 v[130:131], s[6:7], 0, v[148:149]
	s_add_i32 m0, s33, 0x2000
	s_nop 0
	global_load_lds_dwordx4 v[130:131], off
	s_waitcnt vmcnt(6)
	s_barrier
	s_setprio 0
	v_mfma_f32_16x16x32_bf16 v[54:57], v[196:199], v[156:159], v[54:57]
	v_mfma_f32_16x16x32_bf16 v[50:53], v[204:207], v[156:159], v[50:53]
	v_mfma_f32_16x16x32_bf16 v[38:41], v[196:199], v[164:167], v[38:41]
	v_mfma_f32_16x16x32_bf16 v[34:37], v[204:207], v[164:167], v[34:37]
	v_mfma_f32_16x16x32_bf16 v[22:25], v[196:199], v[172:175], v[22:25]
	v_mfma_f32_16x16x32_bf16 v[18:21], v[204:207], v[172:175], v[18:21]
	v_mfma_f32_16x16x32_bf16 v[6:9], v[196:199], v[188:191], v[6:9]
	v_mfma_f32_16x16x32_bf16 v[2:5], v[204:207], v[188:191], v[2:5]
	v_mfma_f32_16x16x32_bf16 v[54:57], v[200:203], v[160:163], v[54:57]
	v_mfma_f32_16x16x32_bf16 v[50:53], v[208:211], v[160:163], v[50:53]
	v_mfma_f32_16x16x32_bf16 v[38:41], v[200:203], v[168:171], v[38:41]
	v_mfma_f32_16x16x32_bf16 v[34:37], v[208:211], v[168:171], v[34:37]
	v_mfma_f32_16x16x32_bf16 v[22:25], v[200:203], v[184:187], v[22:25]
	v_mfma_f32_16x16x32_bf16 v[18:21], v[208:211], v[184:187], v[18:21]
	v_mfma_f32_16x16x32_bf16 v[6:9], v[200:203], v[192:195], v[6:9]
	v_mfma_f32_16x16x32_bf16 v[2:5], v[208:211], v[192:195], v[2:5]
	s_setprio 1
	s_add_i32 s33, 0, 0x18000
	v_add_u32_e32 v0, s33, v155
	s_barrier
	ds_read_b128 v[130:133], v0
	ds_read_b128 v[134:137], v0 offset:1024
	ds_read_b128 v[138:141], v0 offset:2048
	ds_read_b128 v[142:145], v0 offset:3072
	s_add_u32 s6, s90, 0x40000
	s_addc_u32 s7, s91, 0
	s_mov_b32 m0, s15
	v_lshl_add_u64 v[196:197], s[6:7], 0, v[146:147]
	ds_read_b128 v[156:159], v231 offset:32768
	ds_read_b128 v[160:163], v231 offset:33792
	ds_read_b128 v[164:167], v231 offset:34816
	ds_read_b128 v[168:171], v231 offset:35840
	ds_read_b128 v[172:175], v231 offset:36864
	ds_read_b128 v[184:187], v231 offset:37888
	ds_read_b128 v[188:191], v231 offset:38912
	ds_read_b128 v[192:195], v231 offset:39936
	global_load_lds_dwordx4 v[196:197], off
	v_lshl_add_u64 v[196:197], s[6:7], 0, v[148:149]
	s_mov_b32 m0, s16
	s_nop 0
	global_load_lds_dwordx4 v[196:197], off
	s_waitcnt lgkmcnt(8)
	s_barrier
	s_waitcnt lgkmcnt(0)
	s_setprio 0
	s_waitcnt lgkmcnt(0)
	v_mfma_f32_16x16x32_bf16 v[126:129], v[130:133], v[156:159], v[126:129]
	v_mfma_f32_16x16x32_bf16 v[122:125], v[138:141], v[156:159], v[122:125]
	v_mfma_f32_16x16x32_bf16 v[110:113], v[130:133], v[164:167], v[110:113]
	v_mfma_f32_16x16x32_bf16 v[106:109], v[138:141], v[164:167], v[106:109]
	v_mfma_f32_16x16x32_bf16 v[94:97], v[130:133], v[172:175], v[94:97]
	v_mfma_f32_16x16x32_bf16 v[90:93], v[138:141], v[172:175], v[90:93]
	v_mfma_f32_16x16x32_bf16 v[78:81], v[130:133], v[188:191], v[78:81]
	v_mfma_f32_16x16x32_bf16 v[74:77], v[138:141], v[188:191], v[74:77]
	v_mfma_f32_16x16x32_bf16 v[126:129], v[134:137], v[160:163], v[126:129]
	v_mfma_f32_16x16x32_bf16 v[122:125], v[142:145], v[160:163], v[122:125]
	v_mfma_f32_16x16x32_bf16 v[110:113], v[134:137], v[168:171], v[110:113]
	v_mfma_f32_16x16x32_bf16 v[106:109], v[142:145], v[168:171], v[106:109]
	v_mfma_f32_16x16x32_bf16 v[94:97], v[134:137], v[184:187], v[94:97]
	v_mfma_f32_16x16x32_bf16 v[90:93], v[142:145], v[184:187], v[90:93]
	v_mfma_f32_16x16x32_bf16 v[78:81], v[134:137], v[192:195], v[78:81]
	v_mfma_f32_16x16x32_bf16 v[74:77], v[142:145], v[192:195], v[74:77]
	s_setprio 1
	s_barrier
	s_add_i32 s90, 0, 0x1c000
	s_add_i32 s6, s33, s11
	v_add_u32_e32 v0, s90, v155
	v_lshl_add_u64 v[176:177], v[176:177], 0, s[24:25]
	s_mov_b32 m0, s6
	ds_read_b128 v[196:199], v0
	ds_read_b128 v[200:203], v0 offset:1024
	ds_read_b128 v[204:207], v0 offset:2048
	ds_read_b128 v[208:211], v0 offset:3072
	global_load_lds_dwordx4 v[176:177], off
	v_lshl_add_u64 v[176:177], v[180:181], 0, s[24:25]
	s_add_i32 m0, s6, 0x2000
	s_nop 0
	global_load_lds_dwordx4 v[176:177], off
	s_barrier
	s_waitcnt lgkmcnt(0)
	s_setprio 0
	s_waitcnt lgkmcnt(0)
	v_mfma_f32_16x16x32_bf16 v[118:121], v[196:199], v[156:159], v[118:121]
	v_mfma_f32_16x16x32_bf16 v[114:117], v[204:207], v[156:159], v[114:117]
	v_mfma_f32_16x16x32_bf16 v[102:105], v[196:199], v[164:167], v[102:105]
	v_mfma_f32_16x16x32_bf16 v[98:101], v[204:207], v[164:167], v[98:101]
	v_mfma_f32_16x16x32_bf16 v[86:89], v[196:199], v[172:175], v[86:89]
	v_mfma_f32_16x16x32_bf16 v[82:85], v[204:207], v[172:175], v[82:85]
	v_mfma_f32_16x16x32_bf16 v[70:73], v[196:199], v[188:191], v[70:73]
	v_mfma_f32_16x16x32_bf16 v[66:69], v[204:207], v[188:191], v[66:69]
	v_mfma_f32_16x16x32_bf16 v[118:121], v[200:203], v[160:163], v[118:121]
	v_mfma_f32_16x16x32_bf16 v[114:117], v[208:211], v[160:163], v[114:117]
	v_mfma_f32_16x16x32_bf16 v[102:105], v[200:203], v[168:171], v[102:105]
	v_mfma_f32_16x16x32_bf16 v[98:101], v[208:211], v[168:171], v[98:101]
	v_mfma_f32_16x16x32_bf16 v[86:89], v[200:203], v[184:187], v[86:89]
	v_mfma_f32_16x16x32_bf16 v[82:85], v[208:211], v[184:187], v[82:85]
	v_mfma_f32_16x16x32_bf16 v[70:73], v[200:203], v[192:195], v[70:73]
	v_mfma_f32_16x16x32_bf16 v[66:69], v[208:211], v[192:195], v[66:69]
	s_setprio 1
	s_mov_b32 m0, s18
	v_lshl_add_u64 v[176:177], v[212:213], 0, s[24:25]
	s_barrier
	ds_read_b128 v[156:159], v231 offset:49152
	ds_read_b128 v[160:163], v231 offset:50176
	ds_read_b128 v[164:167], v231 offset:51200
	ds_read_b128 v[168:171], v231 offset:52224
	ds_read_b128 v[172:175], v231 offset:53248
	ds_read_b128 v[184:187], v231 offset:54272
	ds_read_b128 v[188:191], v231 offset:55296
	ds_read_b128 v[192:195], v231 offset:56320
	global_load_lds_dwordx4 v[176:177], off
	v_lshl_add_u64 v[176:177], v[214:215], 0, s[24:25]
	s_mov_b32 m0, s19
	s_nop 0
	global_load_lds_dwordx4 v[176:177], off
	s_barrier
	s_waitcnt lgkmcnt(0)
	s_setprio 0
	s_waitcnt lgkmcnt(0)
	v_mfma_f32_16x16x32_bf16 v[62:65], v[130:133], v[156:159], v[62:65]
	v_mfma_f32_16x16x32_bf16 v[58:61], v[138:141], v[156:159], v[58:61]
	v_mfma_f32_16x16x32_bf16 v[46:49], v[130:133], v[164:167], v[46:49]
	v_mfma_f32_16x16x32_bf16 v[42:45], v[138:141], v[164:167], v[42:45]
	v_mfma_f32_16x16x32_bf16 v[30:33], v[130:133], v[172:175], v[30:33]
	v_mfma_f32_16x16x32_bf16 v[26:29], v[138:141], v[172:175], v[26:29]
	v_mfma_f32_16x16x32_bf16 v[14:17], v[130:133], v[188:191], v[14:17]
	v_mfma_f32_16x16x32_bf16 v[10:13], v[138:141], v[188:191], v[10:13]
	v_mfma_f32_16x16x32_bf16 v[62:65], v[134:137], v[160:163], v[62:65]
	v_mfma_f32_16x16x32_bf16 v[58:61], v[142:145], v[160:163], v[58:61]
	v_mfma_f32_16x16x32_bf16 v[46:49], v[134:137], v[168:171], v[46:49]
	v_mfma_f32_16x16x32_bf16 v[42:45], v[142:145], v[168:171], v[42:45]
	v_mfma_f32_16x16x32_bf16 v[30:33], v[134:137], v[184:187], v[30:33]
	v_mfma_f32_16x16x32_bf16 v[26:29], v[142:145], v[184:187], v[26:29]
	v_mfma_f32_16x16x32_bf16 v[14:17], v[134:137], v[192:195], v[14:17]
	v_mfma_f32_16x16x32_bf16 v[10:13], v[142:145], v[192:195], v[10:13]
	s_setprio 1
	s_barrier
	s_add_u32 s6, s62, 0x40080
	s_addc_u32 s7, s63, 0
	s_add_i32 s33, s90, s11
	v_lshl_add_u64 v[130:131], s[6:7], 0, v[146:147]
	s_mov_b32 m0, s33
	s_nop 0
	global_load_lds_dwordx4 v[130:131], off
	v_lshl_add_u64 v[130:131], s[6:7], 0, v[148:149]
	s_add_i32 m0, s33, 0x2000
	s_nop 0
	global_load_lds_dwordx4 v[130:131], off
	s_waitcnt vmcnt(6)
	s_barrier
	s_setprio 0
	v_mfma_f32_16x16x32_bf16 v[54:57], v[196:199], v[156:159], v[54:57]
	v_mfma_f32_16x16x32_bf16 v[50:53], v[204:207], v[156:159], v[50:53]
	v_mfma_f32_16x16x32_bf16 v[38:41], v[196:199], v[164:167], v[38:41]
	v_mfma_f32_16x16x32_bf16 v[34:37], v[204:207], v[164:167], v[34:37]
	v_mfma_f32_16x16x32_bf16 v[22:25], v[196:199], v[172:175], v[22:25]
	v_mfma_f32_16x16x32_bf16 v[18:21], v[204:207], v[172:175], v[18:21]
	v_mfma_f32_16x16x32_bf16 v[6:9], v[196:199], v[188:191], v[6:9]
	v_mfma_f32_16x16x32_bf16 v[2:5], v[204:207], v[188:191], v[2:5]
	v_mfma_f32_16x16x32_bf16 v[54:57], v[200:203], v[160:163], v[54:57]
	v_mfma_f32_16x16x32_bf16 v[50:53], v[208:211], v[160:163], v[50:53]
	v_mfma_f32_16x16x32_bf16 v[38:41], v[200:203], v[168:171], v[38:41]
	v_mfma_f32_16x16x32_bf16 v[34:37], v[208:211], v[168:171], v[34:37]
	v_mfma_f32_16x16x32_bf16 v[22:25], v[200:203], v[184:187], v[22:25]
	v_mfma_f32_16x16x32_bf16 v[18:21], v[208:211], v[184:187], v[18:21]
	v_mfma_f32_16x16x32_bf16 v[6:9], v[200:203], v[192:195], v[6:9]
	v_mfma_f32_16x16x32_bf16 v[2:5], v[208:211], v[192:195], v[2:5]
	s_setprio 1
	s_add_i32 vcc_hi, vcc_hi, 2
	s_add_u32 s2, s2, 0x100
	s_addc_u32 s3, s3, 0
	s_add_u32 s69, s69, 0x100
	s_addc_u32 vcc_lo, vcc_lo, 0
	s_cmp_gt_u32 vcc_hi, 13
	s_barrier
	s_cbranch_scc0 .LBB0_179
	s_cmp_gt_i32 s72, 17
	s_cbranch_scc0 .LBB0_182
	s_and_b32 s1, s72, 0x7ffffffe
	s_cmp_gt_u32 s72, 25
	s_cselect_b32 s2, 3, 0
	s_cmp_lg_u32 s1, 22
	s_cselect_b32 s1, s2, 4
	s_cmp_eq_u32 s72, 19
	s_cselect_b64 vcc, -1, 0
	v_mov_b32_e32 v0, 0x3e000000
	s_and_b64 s[2:3], vcc, exec
	v_cndmask_b32_e32 v154, 1.0, v0, vcc
	s_cselect_b32 s39, 2, s1
	s_movk_i32 s94, 0x2000
	s_mov_b32 s1, 0
	s_cbranch_execz .LBB0_183
	s_branch .LBB0_188

.LBB0_528:
	s_add_u32 s6, s62, 0xfffe0080
	s_addc_u32 s33, s63, -1
	s_add_i32 s72, 0, 0x10000
	v_add_u32_e32 v0, s72, v184
	ds_read_b128 v[130:133], v0
	ds_read_b128 v[134:137], v0 offset:1024
	ds_read_b128 v[138:141], v0 offset:2048
	ds_read_b128 v[142:145], v0 offset:3072
	s_cmp_eq_u32 s69, 4
	s_cselect_b32 vcc_hi, s21, s33
	s_cselect_b32 vcc_lo, s22, s6
	s_cselect_b32 s91, s23, s48
	s_cselect_b32 s90, s39, s47
	v_lshl_add_u64 v[180:181], s[62:63], 0, v[166:167]
	s_add_i32 m0, s3, 0xc000
	ds_read_b128 v[146:149], v201
	ds_read_b128 v[150:153], v201 offset:1024
	ds_read_b128 v[154:157], v201 offset:2048
	ds_read_b128 v[158:161], v201 offset:3072
	ds_read_b128 v[170:173], v201 offset:4096
	ds_read_b128 v[174:177], v201 offset:5120
	ds_read_b128 v[202:205], v201 offset:6144
	ds_read_b128 v[206:209], v201 offset:7168
	global_load_lds_dwordx4 v[180:181], off
	v_lshl_add_u64 v[180:181], s[62:63], 0, v[168:169]
	s_add_i32 m0, s3, 0xe000
	s_nop 0
	global_load_lds_dwordx4 v[180:181], off
	s_waitcnt lgkmcnt(8)
	s_barrier
	s_waitcnt lgkmcnt(0)
	s_setprio 0
	s_waitcnt lgkmcnt(0)
	v_mfma_f32_16x16x32_bf16 v[126:129], v[130:133], v[146:149], v[126:129]
	v_mfma_f32_16x16x32_bf16 v[122:125], v[138:141], v[146:149], v[122:125]
	v_mfma_f32_16x16x32_bf16 v[110:113], v[130:133], v[154:157], v[110:113]
	v_mfma_f32_16x16x32_bf16 v[106:109], v[138:141], v[154:157], v[106:109]
	v_mfma_f32_16x16x32_bf16 v[94:97], v[130:133], v[170:173], v[94:97]
	v_mfma_f32_16x16x32_bf16 v[90:93], v[138:141], v[170:173], v[90:93]
	v_mfma_f32_16x16x32_bf16 v[78:81], v[130:133], v[202:205], v[78:81]
	v_mfma_f32_16x16x32_bf16 v[74:77], v[138:141], v[202:205], v[74:77]
	v_mfma_f32_16x16x32_bf16 v[126:129], v[134:137], v[150:153], v[126:129]
	v_mfma_f32_16x16x32_bf16 v[122:125], v[142:145], v[150:153], v[122:125]
	v_mfma_f32_16x16x32_bf16 v[110:113], v[134:137], v[158:161], v[110:113]
	v_mfma_f32_16x16x32_bf16 v[106:109], v[142:145], v[158:161], v[106:109]
	v_mfma_f32_16x16x32_bf16 v[94:97], v[134:137], v[174:177], v[94:97]
	v_mfma_f32_16x16x32_bf16 v[90:93], v[142:145], v[174:177], v[90:93]
	v_mfma_f32_16x16x32_bf16 v[78:81], v[134:137], v[206:209], v[78:81]
	v_mfma_f32_16x16x32_bf16 v[74:77], v[142:145], v[206:209], v[74:77]
	s_setprio 1
	s_barrier
	s_add_i32 s6, 0, 0x14000
	s_add_i32 s33, s72, s14
	v_add_u32_e32 v0, s6, v184
	v_lshl_add_u64 v[180:181], s[90:91], 0, v[162:163]
	s_mov_b32 m0, s33
	ds_read_b128 v[210:213], v0
	ds_read_b128 v[214:217], v0 offset:1024
	ds_read_b128 v[218:221], v0 offset:2048
	ds_read_b128 v[222:225], v0 offset:3072
	global_load_lds_dwordx4 v[180:181], off
	v_lshl_add_u64 v[226:227], s[90:91], 0, v[164:165]
	s_add_i32 m0, s33, 0x2000
	s_nop 0
	global_load_lds_dwordx4 v[226:227], off
	s_barrier
	s_waitcnt lgkmcnt(0)
	s_setprio 0
	s_waitcnt lgkmcnt(0)
	v_mfma_f32_16x16x32_bf16 v[118:121], v[210:213], v[146:149], v[118:121]
	v_mfma_f32_16x16x32_bf16 v[114:117], v[218:221], v[146:149], v[114:117]
	v_mfma_f32_16x16x32_bf16 v[102:105], v[210:213], v[154:157], v[102:105]
	v_mfma_f32_16x16x32_bf16 v[98:101], v[218:221], v[154:157], v[98:101]
	v_mfma_f32_16x16x32_bf16 v[86:89], v[210:213], v[170:173], v[86:89]
	v_mfma_f32_16x16x32_bf16 v[82:85], v[218:221], v[170:173], v[82:85]
	v_mfma_f32_16x16x32_bf16 v[70:73], v[210:213], v[202:205], v[70:73]
	v_mfma_f32_16x16x32_bf16 v[66:69], v[218:221], v[202:205], v[66:69]
	v_mfma_f32_16x16x32_bf16 v[118:121], v[214:217], v[150:153], v[118:121]
	v_mfma_f32_16x16x32_bf16 v[114:117], v[222:225], v[150:153], v[114:117]
	v_mfma_f32_16x16x32_bf16 v[102:105], v[214:217], v[158:161], v[102:105]
	v_mfma_f32_16x16x32_bf16 v[98:101], v[222:225], v[158:161], v[98:101]
	v_mfma_f32_16x16x32_bf16 v[86:89], v[214:217], v[174:177], v[86:89]
	v_mfma_f32_16x16x32_bf16 v[82:85], v[222:225], v[174:177], v[82:85]
	v_mfma_f32_16x16x32_bf16 v[70:73], v[214:217], v[206:209], v[70:73]
	v_mfma_f32_16x16x32_bf16 v[66:69], v[222:225], v[206:209], v[66:69]
	s_setprio 1
	s_mov_b32 m0, s3
	v_lshl_add_u64 v[240:241], vcc, 0, v[162:163]
	s_barrier
	ds_read_b128 v[146:149], v201 offset:16384
	ds_read_b128 v[150:153], v201 offset:17408
	ds_read_b128 v[154:157], v201 offset:18432
	ds_read_b128 v[158:161], v201 offset:19456
	ds_read_b128 v[170:173], v201 offset:20480
	ds_read_b128 v[174:177], v201 offset:21504
	ds_read_b128 v[202:205], v201 offset:22528
	ds_read_b128 v[206:209], v201 offset:23552
	global_load_lds_dwordx4 v[240:241], off
	v_lshl_add_u64 v[244:245], vcc, 0, v[164:165]
	s_mov_b32 m0, s15
	s_nop 0
	global_load_lds_dwordx4 v[244:245], off
	s_barrier
	s_waitcnt lgkmcnt(0)
	s_setprio 0
	s_waitcnt lgkmcnt(0)
	v_mfma_f32_16x16x32_bf16 v[62:65], v[130:133], v[146:149], v[62:65]
	v_mfma_f32_16x16x32_bf16 v[58:61], v[138:141], v[146:149], v[58:61]
	v_mfma_f32_16x16x32_bf16 v[46:49], v[130:133], v[154:157], v[46:49]
	v_mfma_f32_16x16x32_bf16 v[42:45], v[138:141], v[154:157], v[42:45]
	v_mfma_f32_16x16x32_bf16 v[30:33], v[130:133], v[170:173], v[30:33]
	v_mfma_f32_16x16x32_bf16 v[26:29], v[138:141], v[170:173], v[26:29]
	v_mfma_f32_16x16x32_bf16 v[14:17], v[130:133], v[202:205], v[14:17]
	v_mfma_f32_16x16x32_bf16 v[10:13], v[138:141], v[202:205], v[10:13]
	v_mfma_f32_16x16x32_bf16 v[62:65], v[134:137], v[150:153], v[62:65]
	v_mfma_f32_16x16x32_bf16 v[58:61], v[142:145], v[150:153], v[58:61]
	v_mfma_f32_16x16x32_bf16 v[46:49], v[134:137], v[158:161], v[46:49]
	v_mfma_f32_16x16x32_bf16 v[42:45], v[142:145], v[158:161], v[42:45]
	v_mfma_f32_16x16x32_bf16 v[30:33], v[134:137], v[174:177], v[30:33]
	v_mfma_f32_16x16x32_bf16 v[26:29], v[142:145], v[174:177], v[26:29]
	v_mfma_f32_16x16x32_bf16 v[14:17], v[134:137], v[206:209], v[14:17]
	v_mfma_f32_16x16x32_bf16 v[10:13], v[142:145], v[206:209], v[10:13]
	s_setprio 1
	s_barrier
	s_add_u32 s72, s90, 0x20000
	s_addc_u32 s73, s91, 0
	s_add_i32 s6, s6, s14
	v_lshl_add_u64 v[130:131], s[72:73], 0, v[162:163]
	s_mov_b32 m0, s6
	s_nop 0
	global_load_lds_dwordx4 v[130:131], off
	v_lshl_add_u64 v[130:131], s[72:73], 0, v[164:165]
	s_add_i32 m0, s6, 0x2000
	s_nop 0
	global_load_lds_dwordx4 v[130:131], off
	s_waitcnt vmcnt(6)
	s_barrier
	s_setprio 0
	v_mfma_f32_16x16x32_bf16 v[54:57], v[210:213], v[146:149], v[54:57]
	v_mfma_f32_16x16x32_bf16 v[50:53], v[218:221], v[146:149], v[50:53]
	v_mfma_f32_16x16x32_bf16 v[38:41], v[210:213], v[154:157], v[38:41]
	v_mfma_f32_16x16x32_bf16 v[34:37], v[218:221], v[154:157], v[34:37]
	v_mfma_f32_16x16x32_bf16 v[22:25], v[210:213], v[170:173], v[22:25]
	v_mfma_f32_16x16x32_bf16 v[18:21], v[218:221], v[170:173], v[18:21]
	v_mfma_f32_16x16x32_bf16 v[6:9], v[210:213], v[202:205], v[6:9]
	v_mfma_f32_16x16x32_bf16 v[2:5], v[218:221], v[202:205], v[2:5]
	v_mfma_f32_16x16x32_bf16 v[54:57], v[214:217], v[150:153], v[54:57]
	v_mfma_f32_16x16x32_bf16 v[50:53], v[222:225], v[150:153], v[50:53]
	v_mfma_f32_16x16x32_bf16 v[38:41], v[214:217], v[158:161], v[38:41]
	v_mfma_f32_16x16x32_bf16 v[34:37], v[222:225], v[158:161], v[34:37]
	v_mfma_f32_16x16x32_bf16 v[22:25], v[214:217], v[174:177], v[22:25]
	v_mfma_f32_16x16x32_bf16 v[18:21], v[222:225], v[174:177], v[18:21]
	v_mfma_f32_16x16x32_bf16 v[6:9], v[214:217], v[206:209], v[6:9]
	v_mfma_f32_16x16x32_bf16 v[2:5], v[222:225], v[206:209], v[2:5]
	s_setprio 1
	s_add_i32 s6, 0, 0x18000
	v_add_u32_e32 v0, s6, v184
	s_barrier
	ds_read_b128 v[130:133], v0
	ds_read_b128 v[134:137], v0 offset:1024
	ds_read_b128 v[138:141], v0 offset:2048
	ds_read_b128 v[142:145], v0 offset:3072
	s_add_u32 s72, vcc_lo, 0x20000
	s_addc_u32 s73, vcc_hi, 0
	s_mov_b32 m0, s16
	v_lshl_add_u64 v[210:211], s[72:73], 0, v[162:163]
	ds_read_b128 v[146:149], v201 offset:32768
	ds_read_b128 v[150:153], v201 offset:33792
	ds_read_b128 v[154:157], v201 offset:34816
	ds_read_b128 v[158:161], v201 offset:35840
	ds_read_b128 v[170:173], v201 offset:36864
	ds_read_b128 v[174:177], v201 offset:37888
	ds_read_b128 v[202:205], v201 offset:38912
	ds_read_b128 v[206:209], v201 offset:39936
	global_load_lds_dwordx4 v[210:211], off
	v_lshl_add_u64 v[210:211], s[72:73], 0, v[164:165]
	s_mov_b32 m0, s17
	s_nop 0
	global_load_lds_dwordx4 v[210:211], off
	s_waitcnt lgkmcnt(8)
	s_barrier
	s_waitcnt lgkmcnt(0)
	s_setprio 0
	s_waitcnt lgkmcnt(0)
	v_mfma_f32_16x16x32_bf16 v[126:129], v[130:133], v[146:149], v[126:129]
	v_mfma_f32_16x16x32_bf16 v[122:125], v[138:141], v[146:149], v[122:125]
	v_mfma_f32_16x16x32_bf16 v[110:113], v[130:133], v[154:157], v[110:113]
	v_mfma_f32_16x16x32_bf16 v[106:109], v[138:141], v[154:157], v[106:109]
	v_mfma_f32_16x16x32_bf16 v[94:97], v[130:133], v[170:173], v[94:97]
	v_mfma_f32_16x16x32_bf16 v[90:93], v[138:141], v[170:173], v[90:93]
	v_mfma_f32_16x16x32_bf16 v[78:81], v[130:133], v[202:205], v[78:81]
	v_mfma_f32_16x16x32_bf16 v[74:77], v[138:141], v[202:205], v[74:77]
	v_mfma_f32_16x16x32_bf16 v[126:129], v[134:137], v[150:153], v[126:129]
	v_mfma_f32_16x16x32_bf16 v[122:125], v[142:145], v[150:153], v[122:125]
	v_mfma_f32_16x16x32_bf16 v[110:113], v[134:137], v[158:161], v[110:113]
	v_mfma_f32_16x16x32_bf16 v[106:109], v[142:145], v[158:161], v[106:109]
	v_mfma_f32_16x16x32_bf16 v[94:97], v[134:137], v[174:177], v[94:97]
	v_mfma_f32_16x16x32_bf16 v[90:93], v[142:145], v[174:177], v[90:93]
	v_mfma_f32_16x16x32_bf16 v[78:81], v[134:137], v[206:209], v[78:81]
	v_mfma_f32_16x16x32_bf16 v[74:77], v[142:145], v[206:209], v[74:77]
	s_setprio 1
	s_barrier
	s_add_i32 s33, 0, 0x1c000
	s_add_i32 s6, s6, s14
	v_add_u32_e32 v0, s33, v184
	v_lshl_add_u64 v[180:181], v[180:181], 0, s[24:25]
	s_mov_b32 m0, s6
	ds_read_b128 v[210:213], v0
	ds_read_b128 v[214:217], v0 offset:1024
	ds_read_b128 v[218:221], v0 offset:2048
	ds_read_b128 v[222:225], v0 offset:3072
	global_load_lds_dwordx4 v[180:181], off
	v_lshl_add_u64 v[180:181], v[226:227], 0, s[24:25]
	s_add_i32 m0, s6, 0x2000
	s_nop 0
	global_load_lds_dwordx4 v[180:181], off
	s_barrier
	s_waitcnt lgkmcnt(0)
	s_setprio 0
	s_waitcnt lgkmcnt(0)
	v_mfma_f32_16x16x32_bf16 v[118:121], v[210:213], v[146:149], v[118:121]
	v_mfma_f32_16x16x32_bf16 v[114:117], v[218:221], v[146:149], v[114:117]
	v_mfma_f32_16x16x32_bf16 v[102:105], v[210:213], v[154:157], v[102:105]
	v_mfma_f32_16x16x32_bf16 v[98:101], v[218:221], v[154:157], v[98:101]
	v_mfma_f32_16x16x32_bf16 v[86:89], v[210:213], v[170:173], v[86:89]
	v_mfma_f32_16x16x32_bf16 v[82:85], v[218:221], v[170:173], v[82:85]
	v_mfma_f32_16x16x32_bf16 v[70:73], v[210:213], v[202:205], v[70:73]
	v_mfma_f32_16x16x32_bf16 v[66:69], v[218:221], v[202:205], v[66:69]
	v_mfma_f32_16x16x32_bf16 v[118:121], v[214:217], v[150:153], v[118:121]
	v_mfma_f32_16x16x32_bf16 v[114:117], v[222:225], v[150:153], v[114:117]
	v_mfma_f32_16x16x32_bf16 v[102:105], v[214:217], v[158:161], v[102:105]
	v_mfma_f32_16x16x32_bf16 v[98:101], v[222:225], v[158:161], v[98:101]
	v_mfma_f32_16x16x32_bf16 v[86:89], v[214:217], v[174:177], v[86:89]
	v_mfma_f32_16x16x32_bf16 v[82:85], v[222:225], v[174:177], v[82:85]
	v_mfma_f32_16x16x32_bf16 v[70:73], v[214:217], v[206:209], v[70:73]
	v_mfma_f32_16x16x32_bf16 v[66:69], v[222:225], v[206:209], v[66:69]
	s_setprio 1
	s_mov_b32 m0, s7
	v_lshl_add_u64 v[180:181], v[240:241], 0, s[24:25]
	s_barrier
	ds_read_b128 v[146:149], v201 offset:49152
	ds_read_b128 v[150:153], v201 offset:50176
	ds_read_b128 v[154:157], v201 offset:51200
	ds_read_b128 v[158:161], v201 offset:52224
	ds_read_b128 v[170:173], v201 offset:53248
	ds_read_b128 v[174:177], v201 offset:54272
	ds_read_b128 v[202:205], v201 offset:55296
	ds_read_b128 v[206:209], v201 offset:56320
	global_load_lds_dwordx4 v[180:181], off
	v_lshl_add_u64 v[180:181], v[244:245], 0, s[24:25]
	s_mov_b32 m0, s18
	s_nop 0
	global_load_lds_dwordx4 v[180:181], off
	s_barrier
	s_waitcnt lgkmcnt(0)
	s_setprio 0
	s_waitcnt lgkmcnt(0)
	v_mfma_f32_16x16x32_bf16 v[62:65], v[130:133], v[146:149], v[62:65]
	v_mfma_f32_16x16x32_bf16 v[58:61], v[138:141], v[146:149], v[58:61]
	v_mfma_f32_16x16x32_bf16 v[46:49], v[130:133], v[154:157], v[46:49]
	v_mfma_f32_16x16x32_bf16 v[42:45], v[138:141], v[154:157], v[42:45]
	v_mfma_f32_16x16x32_bf16 v[30:33], v[130:133], v[170:173], v[30:33]
	v_mfma_f32_16x16x32_bf16 v[26:29], v[138:141], v[170:173], v[26:29]
	v_mfma_f32_16x16x32_bf16 v[14:17], v[130:133], v[202:205], v[14:17]
	v_mfma_f32_16x16x32_bf16 v[10:13], v[138:141], v[202:205], v[10:13]
	v_mfma_f32_16x16x32_bf16 v[62:65], v[134:137], v[150:153], v[62:65]
	v_mfma_f32_16x16x32_bf16 v[58:61], v[142:145], v[150:153], v[58:61]
	v_mfma_f32_16x16x32_bf16 v[46:49], v[134:137], v[158:161], v[46:49]
	v_mfma_f32_16x16x32_bf16 v[42:45], v[142:145], v[158:161], v[42:45]
	v_mfma_f32_16x16x32_bf16 v[30:33], v[134:137], v[174:177], v[30:33]
	v_mfma_f32_16x16x32_bf16 v[26:29], v[142:145], v[174:177], v[26:29]
	v_mfma_f32_16x16x32_bf16 v[14:17], v[134:137], v[206:209], v[14:17]
	v_mfma_f32_16x16x32_bf16 v[10:13], v[142:145], v[206:209], v[10:13]
	s_setprio 1
	s_barrier
	s_add_u32 s72, s90, 0x20080
	s_addc_u32 s73, s91, 0
	s_add_i32 s6, s33, s14
	v_lshl_add_u64 v[130:131], s[72:73], 0, v[162:163]
	s_mov_b32 m0, s6
	s_nop 0
	global_load_lds_dwordx4 v[130:131], off
	v_lshl_add_u64 v[130:131], s[72:73], 0, v[164:165]
	s_add_i32 m0, s6, 0x2000
	s_nop 0
	global_load_lds_dwordx4 v[130:131], off
	s_waitcnt vmcnt(6)
	s_barrier
	s_setprio 0
	v_mfma_f32_16x16x32_bf16 v[54:57], v[210:213], v[146:149], v[54:57]
	v_mfma_f32_16x16x32_bf16 v[50:53], v[218:221], v[146:149], v[50:53]
	v_mfma_f32_16x16x32_bf16 v[38:41], v[210:213], v[154:157], v[38:41]
	v_mfma_f32_16x16x32_bf16 v[34:37], v[218:221], v[154:157], v[34:37]
	v_mfma_f32_16x16x32_bf16 v[22:25], v[210:213], v[170:173], v[22:25]
	v_mfma_f32_16x16x32_bf16 v[18:21], v[218:221], v[170:173], v[18:21]
	v_mfma_f32_16x16x32_bf16 v[6:9], v[210:213], v[202:205], v[6:9]
	v_mfma_f32_16x16x32_bf16 v[2:5], v[218:221], v[202:205], v[2:5]
	v_mfma_f32_16x16x32_bf16 v[54:57], v[214:217], v[150:153], v[54:57]
	v_mfma_f32_16x16x32_bf16 v[50:53], v[222:225], v[150:153], v[50:53]
	v_mfma_f32_16x16x32_bf16 v[38:41], v[214:217], v[158:161], v[38:41]
	v_mfma_f32_16x16x32_bf16 v[34:37], v[222:225], v[158:161], v[34:37]
	v_mfma_f32_16x16x32_bf16 v[22:25], v[214:217], v[174:177], v[22:25]
	v_mfma_f32_16x16x32_bf16 v[18:21], v[222:225], v[174:177], v[18:21]
	v_mfma_f32_16x16x32_bf16 v[6:9], v[214:217], v[206:209], v[6:9]
	v_mfma_f32_16x16x32_bf16 v[2:5], v[222:225], v[206:209], v[2:5]
	s_setprio 1
	s_add_i32 s69, s69, 2
	s_add_u32 s62, s62, 0x100
	s_addc_u32 s63, s63, 0
	s_add_u32 s47, s47, 0x100
	s_addc_u32 s48, s48, 0
	s_cmp_gt_u32 s69, 5
	s_barrier
	s_cbranch_scc0 .LBB0_528
	s_lshl_b32 s21, s38, 8
	s_ashr_i32 s6, s38, 2
	s_and_b32 s21, s21, 0x300
	s_cmp_lt_u32 s38, 4
	s_cselect_b64 s[62:63], -1, 0
	s_cmp_gt_u32 s38, 3
	s_cselect_b64 s[90:91], -1, 0
	s_lshl_b32 s22, s6, 15
	s_lshl_b32 s2, s2, 8
	s_lshl_b32 s6, s6, 10
	v_or_b32_e32 v132, s21, v200
	s_sub_i32 s2, s2, s22
	s_addk_i32 s6, 0x1a00
	v_add_u32_e32 v0, s6, v132
	v_add_u32_e32 v170, s2, v179
	v_ashrrev_i32_e32 v203, 8, v0
	v_lshrrev_b32_e32 v0, 8, v170
	v_mad_i32_i24 v130, v0, 38, v203
	v_bitop3_b32 v202, s21, v243, v200 bitop3:0xc8
	v_ashrrev_i32_e32 v131, 31, v130
	v_or_b32_e32 v0, v202, v185
	v_lshlrev_b64 v[130:131], 17, v[130:131]
	v_lshl_add_u64 v[130:131], s[40:41], 0, v[130:131]
	v_lshlrev_b32_e32 v0, 1, v0
	v_lshl_add_u64 v[130:131], v[130:131], 0, v[0:1]
	global_load_dwordx4 v[154:157], v[130:131], off
	global_load_dwordx4 v[138:141], v[130:131], off offset:64
	v_lshlrev_b32_e32 v172, 1, v132
	v_mov_b32_e32 v173, v1
	v_lshl_add_u64 v[176:177], s[0:1], 0, v[172:173]
	v_mov_b32_e32 v130, 0
	s_and_b64 vcc, exec, s[62:63]
	v_ashrrev_i32_e32 v171, 31, v170
	v_mov_b32_e32 v146, 0
	v_mov_b32_e32 v147, 0
	v_mov_b32_e32 v148, 0
	v_mov_b32_e32 v149, 0
	v_mov_b32_e32 v158, 0
	v_mov_b32_e32 v159, 0
	v_mov_b32_e32 v160, 0
	v_mov_b32_e32 v161, 0
	s_cbranch_vccnz .LBB0_531
	v_lshlrev_b64 v[132:133], 11, v[170:171]
	v_lshl_add_u64 v[132:133], v[176:177], 0, v[132:133]
	global_load_dwordx4 v[158:161], v[132:133], off
	global_load_dwordx4 v[146:149], v[132:133], off offset:64

.LBB0_618:
	ds_read_b128 v[48:51], v185
	ds_read_b128 v[52:55], v185 offset:1024
	ds_read_b128 v[56:59], v185 offset:2048
	ds_read_b128 v[60:63], v185 offset:3072
	s_add_u32 s47, s48, 0xfffc0080
	s_addc_u32 s50, s49, -1
	s_cmp_eq_u32 s35, 12
	s_cselect_b32 s55, s3, s50
	s_cselect_b32 s54, s21, s47
	s_cselect_b32 s53, s22, s33
	s_cselect_b32 s52, s23, s31
	v_lshl_add_u64 v[180:181], s[48:49], 0, v[164:165]
	s_add_i32 m0, s11, 0xc000
	ds_read_b128 v[144:147], v186
	ds_read_b128 v[148:151], v186 offset:1024
	ds_read_b128 v[152:155], v186 offset:2048
	ds_read_b128 v[156:159], v186 offset:3072
	ds_read_b128 v[172:175], v186 offset:4096
	ds_read_b128 v[176:179], v186 offset:5120
	ds_read_b128 v[188:191], v186 offset:6144
	ds_read_b128 v[192:195], v186 offset:7168
	global_load_lds_dwordx4 v[180:181], off
	v_lshl_add_u64 v[180:181], s[48:49], 0, v[166:167]
	s_add_i32 m0, s11, 0xe000
	s_nop 0
	global_load_lds_dwordx4 v[180:181], off
	s_waitcnt lgkmcnt(8)
	s_barrier
	s_waitcnt lgkmcnt(0)
	s_setprio 0
	s_waitcnt lgkmcnt(0)
	v_mfma_f32_16x16x32_bf16 v[140:143], v[48:51], v[144:147], v[140:143]
	v_mfma_f32_16x16x32_bf16 v[136:139], v[56:59], v[144:147], v[136:139]
	v_mfma_f32_16x16x32_bf16 v[124:127], v[48:51], v[152:155], v[124:127]
	v_mfma_f32_16x16x32_bf16 v[120:123], v[56:59], v[152:155], v[120:123]
	v_mfma_f32_16x16x32_bf16 v[108:111], v[48:51], v[172:175], v[108:111]
	v_mfma_f32_16x16x32_bf16 v[104:107], v[56:59], v[172:175], v[104:107]
	v_mfma_f32_16x16x32_bf16 v[92:95], v[48:51], v[188:191], v[92:95]
	v_mfma_f32_16x16x32_bf16 v[88:91], v[56:59], v[188:191], v[88:91]
	v_mfma_f32_16x16x32_bf16 v[140:143], v[52:55], v[148:151], v[140:143]
	v_mfma_f32_16x16x32_bf16 v[136:139], v[60:63], v[148:151], v[136:139]
	v_mfma_f32_16x16x32_bf16 v[124:127], v[52:55], v[156:159], v[124:127]
	v_mfma_f32_16x16x32_bf16 v[120:123], v[60:63], v[156:159], v[120:123]
	v_mfma_f32_16x16x32_bf16 v[108:111], v[52:55], v[176:179], v[108:111]
	v_mfma_f32_16x16x32_bf16 v[104:107], v[60:63], v[176:179], v[104:107]
	v_mfma_f32_16x16x32_bf16 v[92:95], v[52:55], v[192:195], v[92:95]
	v_mfma_f32_16x16x32_bf16 v[88:91], v[60:63], v[192:195], v[88:91]
	s_setprio 1
	s_barrier
	s_add_i32 s47, s19, s10
	v_lshl_add_u64 v[180:181], s[52:53], 0, v[160:161]
	s_mov_b32 m0, s47
	ds_read_b128 v[196:199], v187
	ds_read_b128 v[200:203], v187 offset:1024
	ds_read_b128 v[204:207], v187 offset:2048
	ds_read_b128 v[208:211], v187 offset:3072
	global_load_lds_dwordx4 v[180:181], off
	v_lshl_add_u64 v[212:213], s[52:53], 0, v[162:163]
	s_add_i32 m0, s47, 0x2000
	s_nop 0
	global_load_lds_dwordx4 v[212:213], off
	s_barrier
	s_waitcnt lgkmcnt(0)
	s_setprio 0
	s_waitcnt lgkmcnt(0)
	v_mfma_f32_16x16x32_bf16 v[132:135], v[196:199], v[144:147], v[132:135]
	v_mfma_f32_16x16x32_bf16 v[128:131], v[204:207], v[144:147], v[128:131]
	v_mfma_f32_16x16x32_bf16 v[116:119], v[196:199], v[152:155], v[116:119]
	v_mfma_f32_16x16x32_bf16 v[112:115], v[204:207], v[152:155], v[112:115]
	v_mfma_f32_16x16x32_bf16 v[100:103], v[196:199], v[172:175], v[100:103]
	v_mfma_f32_16x16x32_bf16 v[96:99], v[204:207], v[172:175], v[96:99]
	v_mfma_f32_16x16x32_bf16 v[84:87], v[196:199], v[188:191], v[84:87]
	v_mfma_f32_16x16x32_bf16 v[80:83], v[204:207], v[188:191], v[80:83]
	v_mfma_f32_16x16x32_bf16 v[132:135], v[200:203], v[148:151], v[132:135]
	v_mfma_f32_16x16x32_bf16 v[128:131], v[208:211], v[148:151], v[128:131]
	v_mfma_f32_16x16x32_bf16 v[116:119], v[200:203], v[156:159], v[116:119]
	v_mfma_f32_16x16x32_bf16 v[112:115], v[208:211], v[156:159], v[112:115]
	v_mfma_f32_16x16x32_bf16 v[100:103], v[200:203], v[176:179], v[100:103]
	v_mfma_f32_16x16x32_bf16 v[96:99], v[208:211], v[176:179], v[96:99]
	v_mfma_f32_16x16x32_bf16 v[84:87], v[200:203], v[192:195], v[84:87]
	v_mfma_f32_16x16x32_bf16 v[80:83], v[208:211], v[192:195], v[80:83]
	s_setprio 1
	s_mov_b32 m0, s11
	v_lshl_add_u64 v[214:215], s[54:55], 0, v[160:161]
	s_barrier
	ds_read_b128 v[144:147], v186 offset:16384
	ds_read_b128 v[148:151], v186 offset:17408
	ds_read_b128 v[152:155], v186 offset:18432
	ds_read_b128 v[156:159], v186 offset:19456
	ds_read_b128 v[172:175], v186 offset:20480
	ds_read_b128 v[176:179], v186 offset:21504
	ds_read_b128 v[188:191], v186 offset:22528
	ds_read_b128 v[192:195], v186 offset:23552
	global_load_lds_dwordx4 v[214:215], off
	v_lshl_add_u64 v[216:217], s[54:55], 0, v[162:163]
	s_mov_b32 m0, s12
	s_nop 0
	global_load_lds_dwordx4 v[216:217], off
	s_barrier
	s_waitcnt lgkmcnt(0)
	s_setprio 0
	s_waitcnt lgkmcnt(0)
	v_mfma_f32_16x16x32_bf16 v[76:79], v[48:51], v[144:147], v[76:79]
	v_mfma_f32_16x16x32_bf16 v[72:75], v[56:59], v[144:147], v[72:75]
	v_mfma_f32_16x16x32_bf16 v[44:47], v[48:51], v[152:155], v[44:47]
	v_mfma_f32_16x16x32_bf16 v[40:43], v[56:59], v[152:155], v[40:43]
	v_mfma_f32_16x16x32_bf16 v[28:31], v[48:51], v[172:175], v[28:31]
	v_mfma_f32_16x16x32_bf16 v[24:27], v[56:59], v[172:175], v[24:27]
	v_mfma_f32_16x16x32_bf16 v[12:15], v[48:51], v[188:191], v[12:15]
	v_mfma_f32_16x16x32_bf16 v[8:11], v[56:59], v[188:191], v[8:11]
	v_mfma_f32_16x16x32_bf16 v[76:79], v[52:55], v[148:151], v[76:79]
	v_mfma_f32_16x16x32_bf16 v[72:75], v[60:63], v[148:151], v[72:75]
	v_mfma_f32_16x16x32_bf16 v[44:47], v[52:55], v[156:159], v[44:47]
	v_mfma_f32_16x16x32_bf16 v[40:43], v[60:63], v[156:159], v[40:43]
	v_mfma_f32_16x16x32_bf16 v[28:31], v[52:55], v[176:179], v[28:31]
	v_mfma_f32_16x16x32_bf16 v[24:27], v[60:63], v[176:179], v[24:27]
	v_mfma_f32_16x16x32_bf16 v[12:15], v[52:55], v[192:195], v[12:15]
	v_mfma_f32_16x16x32_bf16 v[8:11], v[60:63], v[192:195], v[8:11]
	s_setprio 1
	s_barrier
	s_add_u32 s50, s52, 0x40000
	s_addc_u32 s51, s53, 0
	s_add_i32 s47, s20, s10
	v_lshl_add_u64 v[48:49], s[50:51], 0, v[160:161]
	s_mov_b32 m0, s47
	s_nop 0
	global_load_lds_dwordx4 v[48:49], off
	v_lshl_add_u64 v[48:49], s[50:51], 0, v[162:163]
	s_add_i32 m0, s47, 0x2000
	s_nop 0
	global_load_lds_dwordx4 v[48:49], off
	s_waitcnt vmcnt(6)
	s_barrier
	s_setprio 0
	v_mfma_f32_16x16x32_bf16 v[36:39], v[196:199], v[152:155], v[36:39]
	v_mfma_f32_16x16x32_bf16 v[32:35], v[204:207], v[152:155], v[32:35]
	v_mfma_f32_16x16x32_bf16 v[20:23], v[196:199], v[172:175], v[20:23]
	v_mfma_f32_16x16x32_bf16 v[16:19], v[204:207], v[172:175], v[16:19]
	v_mfma_f32_16x16x32_bf16 v[4:7], v[196:199], v[188:191], v[4:7]
	v_mfma_f32_16x16x32_bf16 v[0:3], v[204:207], v[188:191], v[0:3]
	v_mfma_f32_16x16x32_bf16 v[48:51], v[196:199], v[144:147], v[68:71]
	v_mfma_f32_16x16x32_bf16 v[52:55], v[204:207], v[144:147], v[64:67]
	v_mfma_f32_16x16x32_bf16 v[36:39], v[200:203], v[156:159], v[36:39]
	v_mfma_f32_16x16x32_bf16 v[32:35], v[208:211], v[156:159], v[32:35]
	v_mfma_f32_16x16x32_bf16 v[20:23], v[200:203], v[176:179], v[20:23]
	v_mfma_f32_16x16x32_bf16 v[16:19], v[208:211], v[176:179], v[16:19]
	v_mfma_f32_16x16x32_bf16 v[4:7], v[200:203], v[192:195], v[4:7]
	v_mfma_f32_16x16x32_bf16 v[0:3], v[208:211], v[192:195], v[0:3]
	v_mfma_f32_16x16x32_bf16 v[48:51], v[200:203], v[148:151], v[48:51]
	v_mfma_f32_16x16x32_bf16 v[52:55], v[208:211], v[148:151], v[52:55]
	s_setprio 1
	s_add_i32 s47, 0, 0x18000
	v_add_u32_e32 v68, s47, v183
	s_barrier
	ds_read_b128 v[56:59], v68
	ds_read_b128 v[60:63], v68 offset:1024
	ds_read_b128 v[64:67], v68 offset:2048
	ds_read_b128 v[68:71], v68 offset:3072
	s_add_u32 s50, s54, 0x40000
	s_addc_u32 s51, s55, 0
	s_mov_b32 m0, s13
	v_lshl_add_u64 v[196:197], s[50:51], 0, v[160:161]
	ds_read_b128 v[144:147], v186 offset:32768
	ds_read_b128 v[148:151], v186 offset:33792
	ds_read_b128 v[152:155], v186 offset:34816
	ds_read_b128 v[156:159], v186 offset:35840
	ds_read_b128 v[172:175], v186 offset:36864
	ds_read_b128 v[176:179], v186 offset:37888
	ds_read_b128 v[188:191], v186 offset:38912
	ds_read_b128 v[192:195], v186 offset:39936
	global_load_lds_dwordx4 v[196:197], off
	v_lshl_add_u64 v[196:197], s[50:51], 0, v[162:163]
	s_mov_b32 m0, s14
	s_nop 0
	global_load_lds_dwordx4 v[196:197], off
	s_waitcnt lgkmcnt(8)
	s_barrier
	s_waitcnt lgkmcnt(0)
	s_setprio 0
	s_waitcnt lgkmcnt(0)
	v_mfma_f32_16x16x32_bf16 v[140:143], v[56:59], v[144:147], v[140:143]
	v_mfma_f32_16x16x32_bf16 v[136:139], v[64:67], v[144:147], v[136:139]
	v_mfma_f32_16x16x32_bf16 v[124:127], v[56:59], v[152:155], v[124:127]
	v_mfma_f32_16x16x32_bf16 v[120:123], v[64:67], v[152:155], v[120:123]
	v_mfma_f32_16x16x32_bf16 v[108:111], v[56:59], v[172:175], v[108:111]
	v_mfma_f32_16x16x32_bf16 v[104:107], v[64:67], v[172:175], v[104:107]
	v_mfma_f32_16x16x32_bf16 v[92:95], v[56:59], v[188:191], v[92:95]
	v_mfma_f32_16x16x32_bf16 v[88:91], v[64:67], v[188:191], v[88:91]
	v_mfma_f32_16x16x32_bf16 v[140:143], v[60:63], v[148:151], v[140:143]
	v_mfma_f32_16x16x32_bf16 v[136:139], v[68:71], v[148:151], v[136:139]
	v_mfma_f32_16x16x32_bf16 v[124:127], v[60:63], v[156:159], v[124:127]
	v_mfma_f32_16x16x32_bf16 v[120:123], v[68:71], v[156:159], v[120:123]
	v_mfma_f32_16x16x32_bf16 v[108:111], v[60:63], v[176:179], v[108:111]
	v_mfma_f32_16x16x32_bf16 v[104:107], v[68:71], v[176:179], v[104:107]
	v_mfma_f32_16x16x32_bf16 v[92:95], v[60:63], v[192:195], v[92:95]
	v_mfma_f32_16x16x32_bf16 v[88:91], v[68:71], v[192:195], v[88:91]
	s_setprio 1
	s_barrier
	s_add_i32 s54, 0, 0x1c000
	s_add_i32 s47, s47, s10
	v_add_u32_e32 v208, s54, v183
	v_lshl_add_u64 v[180:181], v[180:181], 0, s[28:29]
	s_mov_b32 m0, s47
	ds_read_b128 v[196:199], v208
	ds_read_b128 v[200:203], v208 offset:1024
	ds_read_b128 v[204:207], v208 offset:2048
	ds_read_b128 v[208:211], v208 offset:3072
	global_load_lds_dwordx4 v[180:181], off
	v_lshl_add_u64 v[180:181], v[212:213], 0, s[28:29]
	s_add_i32 m0, s47, 0x2000
	s_nop 0
	global_load_lds_dwordx4 v[180:181], off
	s_barrier
	s_waitcnt lgkmcnt(0)
	s_setprio 0
	s_waitcnt lgkmcnt(0)
	v_mfma_f32_16x16x32_bf16 v[132:135], v[196:199], v[144:147], v[132:135]
	v_mfma_f32_16x16x32_bf16 v[128:131], v[204:207], v[144:147], v[128:131]
	v_mfma_f32_16x16x32_bf16 v[116:119], v[196:199], v[152:155], v[116:119]
	v_mfma_f32_16x16x32_bf16 v[112:115], v[204:207], v[152:155], v[112:115]
	v_mfma_f32_16x16x32_bf16 v[100:103], v[196:199], v[172:175], v[100:103]
	v_mfma_f32_16x16x32_bf16 v[96:99], v[204:207], v[172:175], v[96:99]
	v_mfma_f32_16x16x32_bf16 v[84:87], v[196:199], v[188:191], v[84:87]
	v_mfma_f32_16x16x32_bf16 v[80:83], v[204:207], v[188:191], v[80:83]
	v_mfma_f32_16x16x32_bf16 v[132:135], v[200:203], v[148:151], v[132:135]
	v_mfma_f32_16x16x32_bf16 v[128:131], v[208:211], v[148:151], v[128:131]
	v_mfma_f32_16x16x32_bf16 v[116:119], v[200:203], v[156:159], v[116:119]
	v_mfma_f32_16x16x32_bf16 v[112:115], v[208:211], v[156:159], v[112:115]
	v_mfma_f32_16x16x32_bf16 v[100:103], v[200:203], v[176:179], v[100:103]
	v_mfma_f32_16x16x32_bf16 v[96:99], v[208:211], v[176:179], v[96:99]
	v_mfma_f32_16x16x32_bf16 v[84:87], v[200:203], v[192:195], v[84:87]
	v_mfma_f32_16x16x32_bf16 v[80:83], v[208:211], v[192:195], v[80:83]
	s_setprio 1
	s_mov_b32 m0, s16
	v_lshl_add_u64 v[180:181], v[214:215], 0, s[28:29]
	s_barrier
	ds_read_b128 v[144:147], v186 offset:49152
	ds_read_b128 v[148:151], v186 offset:50176
	ds_read_b128 v[152:155], v186 offset:51200
	ds_read_b128 v[156:159], v186 offset:52224
	ds_read_b128 v[172:175], v186 offset:53248
	ds_read_b128 v[176:179], v186 offset:54272
	ds_read_b128 v[188:191], v186 offset:55296
	ds_read_b128 v[192:195], v186 offset:56320
	global_load_lds_dwordx4 v[180:181], off
	v_lshl_add_u64 v[180:181], v[216:217], 0, s[28:29]
	s_mov_b32 m0, s17
	s_nop 0
	global_load_lds_dwordx4 v[180:181], off
	s_barrier
	s_waitcnt lgkmcnt(0)
	s_setprio 0
	s_waitcnt lgkmcnt(0)
	v_mfma_f32_16x16x32_bf16 v[76:79], v[56:59], v[144:147], v[76:79]
	v_mfma_f32_16x16x32_bf16 v[72:75], v[64:67], v[144:147], v[72:75]
	v_mfma_f32_16x16x32_bf16 v[44:47], v[56:59], v[152:155], v[44:47]
	v_mfma_f32_16x16x32_bf16 v[40:43], v[64:67], v[152:155], v[40:43]
	v_mfma_f32_16x16x32_bf16 v[28:31], v[56:59], v[172:175], v[28:31]
	v_mfma_f32_16x16x32_bf16 v[24:27], v[64:67], v[172:175], v[24:27]
	v_mfma_f32_16x16x32_bf16 v[12:15], v[56:59], v[188:191], v[12:15]
	v_mfma_f32_16x16x32_bf16 v[8:11], v[64:67], v[188:191], v[8:11]
	v_mfma_f32_16x16x32_bf16 v[76:79], v[60:63], v[148:151], v[76:79]
	v_mfma_f32_16x16x32_bf16 v[72:75], v[68:71], v[148:151], v[72:75]
	v_mfma_f32_16x16x32_bf16 v[44:47], v[60:63], v[156:159], v[44:47]
	v_mfma_f32_16x16x32_bf16 v[40:43], v[68:71], v[156:159], v[40:43]
	v_mfma_f32_16x16x32_bf16 v[28:31], v[60:63], v[176:179], v[28:31]
	v_mfma_f32_16x16x32_bf16 v[24:27], v[68:71], v[176:179], v[24:27]
	v_mfma_f32_16x16x32_bf16 v[12:15], v[60:63], v[192:195], v[12:15]
	v_mfma_f32_16x16x32_bf16 v[8:11], v[68:71], v[192:195], v[8:11]
	s_setprio 1
	s_barrier
	s_add_u32 s50, s52, 0x40080
	s_addc_u32 s51, s53, 0
	s_add_i32 s47, s54, s10
	v_lshl_add_u64 v[56:57], s[50:51], 0, v[160:161]
	s_mov_b32 m0, s47
	s_nop 0
	global_load_lds_dwordx4 v[56:57], off
	v_lshl_add_u64 v[56:57], s[50:51], 0, v[162:163]
	s_add_i32 m0, s47, 0x2000
	s_nop 0
	global_load_lds_dwordx4 v[56:57], off
	s_waitcnt vmcnt(6)
	s_barrier
	s_setprio 0
	v_mfma_f32_16x16x32_bf16 v[48:51], v[196:199], v[144:147], v[48:51]
	v_mfma_f32_16x16x32_bf16 v[68:71], v[200:203], v[148:151], v[48:51]
	v_mfma_f32_16x16x32_bf16 v[48:51], v[204:207], v[144:147], v[52:55]
	v_mfma_f32_16x16x32_bf16 v[36:39], v[196:199], v[152:155], v[36:39]
	v_mfma_f32_16x16x32_bf16 v[32:35], v[204:207], v[152:155], v[32:35]
	v_mfma_f32_16x16x32_bf16 v[20:23], v[196:199], v[172:175], v[20:23]
	v_mfma_f32_16x16x32_bf16 v[16:19], v[204:207], v[172:175], v[16:19]
	v_mfma_f32_16x16x32_bf16 v[4:7], v[196:199], v[188:191], v[4:7]
	v_mfma_f32_16x16x32_bf16 v[0:3], v[204:207], v[188:191], v[0:3]
	v_mfma_f32_16x16x32_bf16 v[64:67], v[208:211], v[148:151], v[48:51]
	v_mfma_f32_16x16x32_bf16 v[36:39], v[200:203], v[156:159], v[36:39]
	v_mfma_f32_16x16x32_bf16 v[32:35], v[208:211], v[156:159], v[32:35]
	v_mfma_f32_16x16x32_bf16 v[20:23], v[200:203], v[176:179], v[20:23]
	v_mfma_f32_16x16x32_bf16 v[16:19], v[208:211], v[176:179], v[16:19]
	v_mfma_f32_16x16x32_bf16 v[4:7], v[200:203], v[192:195], v[4:7]
	v_mfma_f32_16x16x32_bf16 v[0:3], v[208:211], v[192:195], v[0:3]
	s_setprio 1
	s_add_i32 s35, s35, 2
	s_add_u32 s48, s48, 0x100
	s_addc_u32 s49, s49, 0
	s_add_u32 s31, s31, 0x100
	s_addc_u32 s33, s33, 0
	s_cmp_gt_u32 s35, 13
	s_barrier
	s_cbranch_scc0 .LBB0_618
	v_and_b32_e32 v145, 64, v229
	v_xor_b32_e32 v144, 16, v229
	v_add_u32_e32 v145, 64, v145
	v_cmp_lt_i32_e32 vcc, v144, v145
	v_lshl_or_b32 v172, s46, 8, v184
	v_ashrrev_i32_e32 v173, 31, v172
	v_cndmask_b32_e32 v144, v229, v144, vcc
	v_lshl_add_u32 v174, s2, 8, v182
	v_lshlrev_b32_e32 v189, 2, v144
	v_xor_b32_e32 v144, 32, v229
	v_lshlrev_b64 v[206:207], 2, v[172:173]
	v_cmp_lt_i32_e32 vcc, v144, v145
	v_ashrrev_i32_e32 v175, 31, v174
	v_lshl_add_u64 v[176:177], s[44:45], 0, v[206:207]
	v_cndmask_b32_e32 v144, v229, v144, vcc
	v_lshlrev_b64 v[208:209], 12, v[174:175]
	v_lshl_add_u64 v[56:57], s[56:57], 0, v[206:207]
	v_lshlrev_b32_e32 v188, 2, v144
	v_lshl_add_u64 v[144:145], v[176:177], 0, v[208:209]
	global_load_dwordx4 v[52:55], v[56:57], off offset:16
	global_load_dwordx4 v[60:63], v[56:57], off
	global_load_dwordx4 v[48:51], v[56:57], off offset:144
	s_nop 0
	global_load_dwordx4 v[56:59], v[56:57], off offset:128
	s_nop 0
	global_load_dwordx4 v[190:193], v[144:145], off offset:16
	global_load_dwordx4 v[194:197], v[144:145], off
	global_load_dwordx4 v[198:201], v[144:145], off offset:144
	global_load_dwordx4 v[202:205], v[144:145], off offset:128
	v_or_b32_e32 v178, 16, v174
	v_ashrrev_i32_e32 v179, 31, v178
	v_lshlrev_b64 v[180:181], 12, v[178:179]
	v_lshl_add_u64 v[148:149], v[176:177], 0, v[180:181]
	global_load_dwordx4 v[152:155], v[148:149], off offset:16
	global_load_dwordx4 v[156:159], v[148:149], off
	global_load_dwordx4 v[144:147], v[148:149], off offset:144
	s_nop 0
	global_load_dwordx4 v[148:151], v[148:149], off offset:128
	s_waitcnt vmcnt(0)
	v_pk_add_f32 v[136:137], v[136:137], v[190:191]
	v_pk_add_f32 v[194:195], v[140:141], v[194:195]
	v_pk_add_f32 v[198:199], v[128:129], v[198:199]
	v_lshl_add_u64 v[128:129], s[78:79], 0, v[208:209]
	v_pk_add_f32 v[196:197], v[142:143], v[196:197]
	v_pk_mul_f32 v[212:213], v[194:195], v[194:195]
	v_pk_add_f32 v[190:191], v[132:133], v[202:203]
	v_lshl_add_u64 v[128:129], v[128:129], 0, v[206:207]
	v_pk_mul_f32 v[210:211], v[196:197], v[196:197]
	v_pk_add_f32 v[138:139], v[138:139], v[192:193]
	v_pk_add_f32 v[192:193], v[134:135], v[204:205]
	v_pk_mul_f32 v[204:205], v[190:191], v[190:191]
	v_pk_add_f32 v[200:201], v[130:131], v[200:201]
	global_store_dwordx4 v[128:129], v[194:197], off nt
	global_store_dwordx4 v[128:129], v[136:139], off offset:16 nt
	global_store_dwordx4 v[128:129], v[190:193], off offset:128 nt
	global_store_dwordx4 v[128:129], v[198:201], off offset:144 nt
	v_pk_mul_f32 v[134:135], v[56:57], v[190:191]
	v_add_f32_e32 v190, v212, v213
	v_add_f32_e32 v190, v210, v190
	v_pk_mul_f32 v[216:217], v[136:137], v[136:137]
	v_add_f32_e32 v190, v211, v190
	v_add_f32_e32 v190, v216, v190
	v_pk_mul_f32 v[214:215], v[138:139], v[138:139]
	v_add_f32_e32 v190, v217, v190
	v_add_f32_e32 v190, v214, v190
	v_add_f32_e32 v190, v215, v190
	v_add_f32_e32 v190, v204, v190
	v_pk_mul_f32 v[202:203], v[192:193], v[192:193]
	v_add_f32_e32 v190, v205, v190
	v_add_f32_e32 v190, v202, v190
	v_pk_mul_f32 v[220:221], v[198:199], v[198:199]
	v_add_f32_e32 v190, v203, v190
	v_add_f32_e32 v190, v220, v190
	v_pk_mul_f32 v[218:219], v[200:201], v[200:201]
	v_add_f32_e32 v190, v221, v190
	v_add_f32_e32 v190, v218, v190
	v_pk_mul_f32 v[128:129], v[62:63], v[196:197]
	v_add_f32_e32 v196, v219, v190
	v_lshlrev_b64 v[190:191], 11, v[174:175]
	v_pk_mul_f32 v[142:143], v[60:61], v[194:195]
	v_pk_mul_f32 v[130:131], v[52:53], v[136:137]
	v_pk_mul_f32 v[132:133], v[54:55], v[138:139]
	v_lshl_add_u64 v[190:191], s[24:25], 0, v[190:191]
	v_pk_mul_f32 v[136:137], v[58:59], v[192:193]
	v_pk_mul_f32 v[138:139], v[48:49], v[198:199]
	v_pk_mul_f32 v[140:141], v[50:51], v[200:201]
	v_lshl_add_u64 v[194:195], v[172:173], 1, v[190:191]
	v_cvt_pk_bf16_f32 v190, v142, v143
	v_cvt_pk_bf16_f32 v191, v128, v129
	v_cvt_pk_bf16_f32 v192, v130, v131
	v_cvt_pk_bf16_f32 v193, v132, v133
	v_cvt_pk_bf16_f32 v128, v134, v135
	v_cvt_pk_bf16_f32 v129, v136, v137
	v_cvt_pk_bf16_f32 v130, v138, v139
	v_cvt_pk_bf16_f32 v131, v140, v141
	global_store_dwordx4 v[194:195], v[190:193], off nt
	global_store_dwordx4 v[194:195], v[128:131], off offset:64 nt
	ds_bpermute_b32 v128, v189, v196
	s_waitcnt lgkmcnt(0)
	v_add_f32_e32 v128, v196, v128
	ds_bpermute_b32 v129, v188, v128
	s_and_saveexec_b64 s[2:3], s[36:37]
	s_cbranch_execz .LBB0_621
	v_lshl_add_u64 v[130:131], v[174:175], 2, s[26:27]
	s_waitcnt lgkmcnt(0)
	v_add_f32_e32 v128, v128, v129
	global_atomic_add_f32 v[130:131], v128, off

.LBB0_703:
	ds_read_b128 v[44:47], v236
	ds_read_b128 v[48:51], v236 offset:1024
	ds_read_b128 v[52:55], v236 offset:2048
	ds_read_b128 v[56:59], v236 offset:3072
	s_add_u32 s0, vcc_lo, 0xfffc0080
	s_addc_u32 s1, vcc_hi, -1
	s_cmp_eq_u32 s59, 12
	s_cselect_b32 s91, s22, s1
	s_cselect_b32 s90, s23, s0
	s_cselect_b32 s1, s3, s57
	s_cselect_b32 s0, s51, s55
	v_lshl_add_u64 v[190:191], vcc, 0, v[166:167]
	s_add_i32 m0, s12, 0xc000
	ds_read_b128 v[68:71], v237
	ds_read_b128 v[72:75], v237 offset:1024
	ds_read_b128 v[76:79], v237 offset:2048
	ds_read_b128 v[80:83], v237 offset:3072
	ds_read_b128 v[174:177], v237 offset:4096
	ds_read_b128 v[178:181], v237 offset:5120
	ds_read_b128 v[182:185], v237 offset:6144
	ds_read_b128 v[186:189], v237 offset:7168
	global_load_lds_dwordx4 v[190:191], off
	v_lshl_add_u64 v[190:191], vcc, 0, v[168:169]
	s_add_i32 m0, s12, 0xe000
	s_nop 0
	global_load_lds_dwordx4 v[190:191], off
	s_waitcnt lgkmcnt(8)
	s_barrier
	s_waitcnt lgkmcnt(0)
	s_setprio 0
	s_waitcnt lgkmcnt(0)
	v_mfma_f32_16x16x32_bf16 v[156:159], v[44:47], v[68:71], v[156:159]
	v_mfma_f32_16x16x32_bf16 v[132:135], v[52:55], v[68:71], v[132:135]
	v_mfma_f32_16x16x32_bf16 v[152:155], v[44:47], v[76:79], v[152:155]
	v_mfma_f32_16x16x32_bf16 v[128:131], v[52:55], v[76:79], v[128:131]
	v_mfma_f32_16x16x32_bf16 v[140:143], v[44:47], v[174:177], v[140:143]
	v_mfma_f32_16x16x32_bf16 v[104:107], v[52:55], v[174:177], v[104:107]
	v_mfma_f32_16x16x32_bf16 v[144:147], v[44:47], v[182:185], v[144:147]
	v_mfma_f32_16x16x32_bf16 v[108:111], v[52:55], v[182:185], v[108:111]
	v_mfma_f32_16x16x32_bf16 v[156:159], v[48:51], v[72:75], v[156:159]
	v_mfma_f32_16x16x32_bf16 v[132:135], v[56:59], v[72:75], v[132:135]
	v_mfma_f32_16x16x32_bf16 v[152:155], v[48:51], v[80:83], v[152:155]
	v_mfma_f32_16x16x32_bf16 v[128:131], v[56:59], v[80:83], v[128:131]
	v_mfma_f32_16x16x32_bf16 v[140:143], v[48:51], v[178:181], v[140:143]
	v_mfma_f32_16x16x32_bf16 v[104:107], v[56:59], v[178:181], v[104:107]
	v_mfma_f32_16x16x32_bf16 v[144:147], v[48:51], v[186:189], v[144:147]
	v_mfma_f32_16x16x32_bf16 v[108:111], v[56:59], v[186:189], v[108:111]
	s_setprio 1
	s_barrier
	s_add_i32 s60, s20, s11
	v_lshl_add_u64 v[214:215], s[0:1], 0, v[160:161]
	s_mov_b32 m0, s60
	ds_read_b128 v[190:193], v238
	ds_read_b128 v[194:197], v238 offset:1024
	ds_read_b128 v[198:201], v238 offset:2048
	ds_read_b128 v[202:205], v238 offset:3072
	global_load_lds_dwordx4 v[214:215], off
	v_lshl_add_u64 v[216:217], s[0:1], 0, v[162:163]
	s_add_i32 m0, s60, 0x2000
	s_nop 0
	global_load_lds_dwordx4 v[216:217], off
	s_barrier
	s_waitcnt lgkmcnt(0)
	s_setprio 0
	s_waitcnt lgkmcnt(0)
	v_mfma_f32_16x16x32_bf16 v[148:151], v[190:193], v[68:71], v[148:151]
	v_mfma_f32_16x16x32_bf16 v[68:71], v[198:201], v[68:71], v[124:127]
	v_mfma_f32_16x16x32_bf16 v[148:151], v[194:197], v[72:75], v[148:151]
	v_mfma_f32_16x16x32_bf16 v[68:71], v[202:205], v[72:75], v[68:71]
	v_mfma_f32_16x16x32_bf16 v[72:75], v[190:193], v[76:79], v[120:123]
	v_mfma_f32_16x16x32_bf16 v[76:79], v[198:201], v[76:79], v[112:115]
	v_mfma_f32_16x16x32_bf16 v[100:103], v[198:201], v[174:177], v[100:103]
	v_mfma_f32_16x16x32_bf16 v[112:115], v[190:193], v[182:185], v[136:139]
	v_mfma_f32_16x16x32_bf16 v[96:99], v[198:201], v[182:185], v[96:99]
	v_mfma_f32_16x16x32_bf16 v[72:75], v[194:197], v[80:83], v[72:75]
	v_mfma_f32_16x16x32_bf16 v[76:79], v[202:205], v[80:83], v[76:79]
	v_mfma_f32_16x16x32_bf16 v[80:83], v[190:193], v[174:177], v[116:119]
	v_mfma_f32_16x16x32_bf16 v[100:103], v[202:205], v[178:181], v[100:103]
	v_mfma_f32_16x16x32_bf16 v[136:139], v[194:197], v[186:189], v[112:115]
	v_mfma_f32_16x16x32_bf16 v[96:99], v[202:205], v[186:189], v[96:99]
	v_mfma_f32_16x16x32_bf16 v[80:83], v[194:197], v[178:181], v[80:83]
	s_setprio 1
	s_mov_b32 m0, s12
	v_lshl_add_u64 v[218:219], s[90:91], 0, v[160:161]
	s_barrier
	ds_read_b128 v[112:115], v237 offset:16384
	ds_read_b128 v[116:119], v237 offset:17408
	ds_read_b128 v[120:123], v237 offset:18432
	ds_read_b128 v[124:127], v237 offset:19456
	ds_read_b128 v[174:177], v237 offset:20480
	ds_read_b128 v[178:181], v237 offset:21504
	ds_read_b128 v[182:185], v237 offset:22528
	ds_read_b128 v[186:189], v237 offset:23552
	global_load_lds_dwordx4 v[218:219], off
	v_lshl_add_u64 v[220:221], s[90:91], 0, v[162:163]
	s_mov_b32 m0, s13
	s_nop 0
	global_load_lds_dwordx4 v[220:221], off
	s_barrier
	s_waitcnt lgkmcnt(0)
	s_setprio 0
	s_waitcnt lgkmcnt(0)
	v_mfma_f32_16x16x32_bf16 v[92:95], v[44:47], v[112:115], v[92:95]
	v_mfma_f32_16x16x32_bf16 v[40:43], v[52:55], v[112:115], v[40:43]
	v_mfma_f32_16x16x32_bf16 v[88:91], v[44:47], v[120:123], v[88:91]
	v_mfma_f32_16x16x32_bf16 v[36:39], v[52:55], v[120:123], v[36:39]
	v_mfma_f32_16x16x32_bf16 v[60:63], v[44:47], v[174:177], v[60:63]
	v_mfma_f32_16x16x32_bf16 v[8:11], v[52:55], v[174:177], v[8:11]
	v_mfma_f32_16x16x32_bf16 v[16:19], v[52:55], v[182:185], v[16:19]
	v_mfma_f32_16x16x32_bf16 v[92:95], v[48:51], v[116:119], v[92:95]
	v_mfma_f32_16x16x32_bf16 v[40:43], v[56:59], v[116:119], v[40:43]
	v_mfma_f32_16x16x32_bf16 v[88:91], v[48:51], v[124:127], v[88:91]
	v_mfma_f32_16x16x32_bf16 v[36:39], v[56:59], v[124:127], v[36:39]
	v_mfma_f32_16x16x32_bf16 v[60:63], v[48:51], v[178:181], v[60:63]
	v_mfma_f32_16x16x32_bf16 v[8:11], v[56:59], v[178:181], v[8:11]
	v_mfma_f32_16x16x32_bf16 v[44:47], v[44:47], v[182:185], v[64:67]
	v_mfma_f32_16x16x32_bf16 v[16:19], v[56:59], v[186:189], v[16:19]
	v_mfma_f32_16x16x32_bf16 v[44:47], v[48:51], v[186:189], v[44:47]
	s_setprio 1
	s_barrier
	s_add_u32 s60, s0, 0x40000
	s_addc_u32 s61, s1, 0
	s_add_i32 s63, s21, s11
	v_lshl_add_u64 v[48:49], s[60:61], 0, v[160:161]
	s_mov_b32 m0, s63
	s_nop 0
	global_load_lds_dwordx4 v[48:49], off
	v_lshl_add_u64 v[48:49], s[60:61], 0, v[162:163]
	s_add_i32 m0, s63, 0x2000
	s_nop 0
	global_load_lds_dwordx4 v[48:49], off
	s_waitcnt vmcnt(6)
	s_barrier
	s_setprio 0
	v_mfma_f32_16x16x32_bf16 v[28:31], v[198:201], v[112:115], v[28:31]
	v_mfma_f32_16x16x32_bf16 v[24:27], v[190:193], v[120:123], v[24:27]
	v_mfma_f32_16x16x32_bf16 v[12:15], v[198:201], v[120:123], v[12:15]
	v_mfma_f32_16x16x32_bf16 v[20:23], v[190:193], v[174:177], v[20:23]
	v_mfma_f32_16x16x32_bf16 v[4:7], v[198:201], v[174:177], v[4:7]
	v_mfma_f32_16x16x32_bf16 v[32:35], v[190:193], v[182:185], v[32:35]
	v_mfma_f32_16x16x32_bf16 v[0:3], v[198:201], v[182:185], v[0:3]
	v_mfma_f32_16x16x32_bf16 v[48:51], v[190:193], v[112:115], v[84:87]
	v_mfma_f32_16x16x32_bf16 v[28:31], v[202:205], v[116:119], v[28:31]
	v_mfma_f32_16x16x32_bf16 v[24:27], v[194:197], v[124:127], v[24:27]
	v_mfma_f32_16x16x32_bf16 v[12:15], v[202:205], v[124:127], v[12:15]
	v_mfma_f32_16x16x32_bf16 v[20:23], v[194:197], v[178:181], v[20:23]
	v_mfma_f32_16x16x32_bf16 v[4:7], v[202:205], v[178:181], v[4:7]
	v_mfma_f32_16x16x32_bf16 v[32:35], v[194:197], v[186:189], v[32:35]
	v_mfma_f32_16x16x32_bf16 v[0:3], v[202:205], v[186:189], v[0:3]
	v_mfma_f32_16x16x32_bf16 v[48:51], v[194:197], v[116:119], v[48:51]
	s_setprio 1
	s_add_i32 s63, 0, 0x18000
	v_add_u32_e32 v64, s63, v232
	s_barrier
	ds_read_b128 v[52:55], v64
	ds_read_b128 v[56:59], v64 offset:1024
	ds_read_b128 v[84:87], v64 offset:2048
	ds_read_b128 v[174:177], v64 offset:3072
	s_add_u32 s60, s90, 0x40000
	s_addc_u32 s61, s91, 0
	s_mov_b32 m0, s14
	v_lshl_add_u64 v[120:121], s[60:61], 0, v[160:161]
	ds_read_b128 v[64:67], v237 offset:32768
	ds_read_b128 v[112:115], v237 offset:33792
	ds_read_b128 v[116:119], v237 offset:34816
	ds_read_b128 v[178:181], v237 offset:35840
	ds_read_b128 v[182:185], v237 offset:36864
	ds_read_b128 v[186:189], v237 offset:37888
	ds_read_b128 v[190:193], v237 offset:38912
	ds_read_b128 v[194:197], v237 offset:39936
	global_load_lds_dwordx4 v[120:121], off
	v_lshl_add_u64 v[120:121], s[60:61], 0, v[162:163]
	s_mov_b32 m0, s15
	s_nop 0
	global_load_lds_dwordx4 v[120:121], off
	s_waitcnt lgkmcnt(8)
	s_barrier
	s_waitcnt lgkmcnt(0)
	s_setprio 0
	s_waitcnt lgkmcnt(0)
	v_mfma_f32_16x16x32_bf16 v[120:123], v[52:55], v[64:67], v[156:159]
	v_mfma_f32_16x16x32_bf16 v[156:159], v[56:59], v[112:115], v[120:123]
	v_mfma_f32_16x16x32_bf16 v[120:123], v[84:87], v[64:67], v[132:135]
	v_mfma_f32_16x16x32_bf16 v[132:135], v[174:177], v[112:115], v[120:123]
	v_mfma_f32_16x16x32_bf16 v[120:123], v[52:55], v[116:119], v[152:155]
	v_mfma_f32_16x16x32_bf16 v[152:155], v[56:59], v[178:181], v[120:123]
	v_mfma_f32_16x16x32_bf16 v[120:123], v[84:87], v[116:119], v[128:131]
	v_mfma_f32_16x16x32_bf16 v[128:131], v[174:177], v[178:181], v[120:123]
	v_mfma_f32_16x16x32_bf16 v[120:123], v[52:55], v[182:185], v[140:143]
	v_mfma_f32_16x16x32_bf16 v[140:143], v[56:59], v[186:189], v[120:123]
	v_mfma_f32_16x16x32_bf16 v[104:107], v[84:87], v[182:185], v[104:107]
	v_mfma_f32_16x16x32_bf16 v[120:123], v[52:55], v[190:193], v[144:147]
	v_mfma_f32_16x16x32_bf16 v[108:111], v[84:87], v[190:193], v[108:111]
	v_mfma_f32_16x16x32_bf16 v[104:107], v[174:177], v[186:189], v[104:107]
	v_mfma_f32_16x16x32_bf16 v[144:147], v[56:59], v[194:197], v[120:123]
	v_mfma_f32_16x16x32_bf16 v[108:111], v[174:177], v[194:197], v[108:111]
	s_setprio 1
	s_barrier
	s_add_i32 s60, 0, 0x1c000
	s_nop 0
	v_add_u32_e32 v120, s60, v232
	s_add_i32 s61, s63, s11
	ds_read_b128 v[198:201], v120
	ds_read_b128 v[202:205], v120 offset:1024
	ds_read_b128 v[206:209], v120 offset:2048
	ds_read_b128 v[210:213], v120 offset:3072
	v_lshl_add_u64 v[120:121], v[214:215], 0, s[52:53]
	s_mov_b32 m0, s61
	s_nop 0
	global_load_lds_dwordx4 v[120:121], off
	v_lshl_add_u64 v[120:121], v[216:217], 0, s[52:53]
	s_add_i32 m0, s61, 0x2000
	s_nop 0
	global_load_lds_dwordx4 v[120:121], off
	s_barrier
	s_waitcnt lgkmcnt(0)
	s_setprio 0
	s_waitcnt lgkmcnt(0)
	v_mfma_f32_16x16x32_bf16 v[120:123], v[198:201], v[64:67], v[148:151]
	v_mfma_f32_16x16x32_bf16 v[64:67], v[206:209], v[64:67], v[68:71]
	v_mfma_f32_16x16x32_bf16 v[124:127], v[210:213], v[112:115], v[64:67]
	v_mfma_f32_16x16x32_bf16 v[64:67], v[198:201], v[116:119], v[72:75]
	v_mfma_f32_16x16x32_bf16 v[148:151], v[202:205], v[112:115], v[120:123]
	v_mfma_f32_16x16x32_bf16 v[120:123], v[202:205], v[178:181], v[64:67]
	v_mfma_f32_16x16x32_bf16 v[64:67], v[206:209], v[116:119], v[76:79]
	v_mfma_f32_16x16x32_bf16 v[112:115], v[210:213], v[178:181], v[64:67]
	v_mfma_f32_16x16x32_bf16 v[64:67], v[198:201], v[182:185], v[80:83]
	v_mfma_f32_16x16x32_bf16 v[116:119], v[202:205], v[186:189], v[64:67]
	v_mfma_f32_16x16x32_bf16 v[64:67], v[206:209], v[182:185], v[100:103]
	v_mfma_f32_16x16x32_bf16 v[100:103], v[210:213], v[186:189], v[64:67]
	v_mfma_f32_16x16x32_bf16 v[64:67], v[198:201], v[190:193], v[136:139]
	v_mfma_f32_16x16x32_bf16 v[136:139], v[202:205], v[194:197], v[64:67]
	v_mfma_f32_16x16x32_bf16 v[64:67], v[206:209], v[190:193], v[96:99]
	v_mfma_f32_16x16x32_bf16 v[96:99], v[210:213], v[194:197], v[64:67]
	s_setprio 1
	s_mov_b32 m0, s17
	s_nop 4
	v_lshl_add_u64 v[64:65], v[218:219], 0, s[52:53]
	s_barrier
	ds_read_b128 v[68:71], v237 offset:49152
	ds_read_b128 v[72:75], v237 offset:50176
	ds_read_b128 v[76:79], v237 offset:51200
	ds_read_b128 v[80:83], v237 offset:52224
	ds_read_b128 v[178:181], v237 offset:53248
	ds_read_b128 v[182:185], v237 offset:54272
	ds_read_b128 v[186:189], v237 offset:55296
	ds_read_b128 v[190:193], v237 offset:56320
	global_load_lds_dwordx4 v[64:65], off
	v_lshl_add_u64 v[64:65], v[220:221], 0, s[52:53]
	s_mov_b32 m0, s18
	s_nop 0
	global_load_lds_dwordx4 v[64:65], off
	s_barrier
	s_waitcnt lgkmcnt(0)
	s_setprio 0
	s_waitcnt lgkmcnt(0)
	v_mfma_f32_16x16x32_bf16 v[64:67], v[52:55], v[68:71], v[92:95]
	v_mfma_f32_16x16x32_bf16 v[92:95], v[56:59], v[72:75], v[64:67]
	v_mfma_f32_16x16x32_bf16 v[40:43], v[84:87], v[68:71], v[40:43]
	v_mfma_f32_16x16x32_bf16 v[64:67], v[52:55], v[76:79], v[88:91]
	v_mfma_f32_16x16x32_bf16 v[36:39], v[84:87], v[76:79], v[36:39]
	v_mfma_f32_16x16x32_bf16 v[60:63], v[52:55], v[178:181], v[60:63]
	v_mfma_f32_16x16x32_bf16 v[8:11], v[84:87], v[178:181], v[8:11]
	v_mfma_f32_16x16x32_bf16 v[44:47], v[52:55], v[186:189], v[44:47]
	v_mfma_f32_16x16x32_bf16 v[16:19], v[84:87], v[186:189], v[16:19]
	v_mfma_f32_16x16x32_bf16 v[40:43], v[174:177], v[72:75], v[40:43]
	v_mfma_f32_16x16x32_bf16 v[88:91], v[56:59], v[80:83], v[64:67]
	v_mfma_f32_16x16x32_bf16 v[36:39], v[174:177], v[80:83], v[36:39]
	v_mfma_f32_16x16x32_bf16 v[60:63], v[56:59], v[182:185], v[60:63]
	v_mfma_f32_16x16x32_bf16 v[8:11], v[174:177], v[182:185], v[8:11]
	v_mfma_f32_16x16x32_bf16 v[64:67], v[56:59], v[190:193], v[44:47]
	v_mfma_f32_16x16x32_bf16 v[16:19], v[174:177], v[190:193], v[16:19]
	s_setprio 1
	s_barrier
	s_add_u32 s0, s0, 0x40080
	s_addc_u32 s1, s1, 0
	s_add_i32 s60, s60, s11
	v_lshl_add_u64 v[44:45], s[0:1], 0, v[160:161]
	s_mov_b32 m0, s60
	s_nop 0
	global_load_lds_dwordx4 v[44:45], off
	v_lshl_add_u64 v[44:45], s[0:1], 0, v[162:163]
	s_add_i32 m0, s60, 0x2000
	s_nop 0
	global_load_lds_dwordx4 v[44:45], off
	s_waitcnt vmcnt(6)
	s_barrier
	s_setprio 0
	v_mfma_f32_16x16x32_bf16 v[44:47], v[198:201], v[68:71], v[48:51]
	v_mfma_f32_16x16x32_bf16 v[28:31], v[206:209], v[68:71], v[28:31]
	v_mfma_f32_16x16x32_bf16 v[24:27], v[198:201], v[76:79], v[24:27]
	v_mfma_f32_16x16x32_bf16 v[12:15], v[206:209], v[76:79], v[12:15]
	v_mfma_f32_16x16x32_bf16 v[20:23], v[198:201], v[178:181], v[20:23]
	v_mfma_f32_16x16x32_bf16 v[4:7], v[206:209], v[178:181], v[4:7]
	v_mfma_f32_16x16x32_bf16 v[32:35], v[198:201], v[186:189], v[32:35]
	v_mfma_f32_16x16x32_bf16 v[0:3], v[206:209], v[186:189], v[0:3]
	v_mfma_f32_16x16x32_bf16 v[84:87], v[202:205], v[72:75], v[44:47]
	v_mfma_f32_16x16x32_bf16 v[28:31], v[210:213], v[72:75], v[28:31]
	v_mfma_f32_16x16x32_bf16 v[24:27], v[202:205], v[80:83], v[24:27]
	v_mfma_f32_16x16x32_bf16 v[12:15], v[210:213], v[80:83], v[12:15]
	v_mfma_f32_16x16x32_bf16 v[20:23], v[202:205], v[182:185], v[20:23]
	v_mfma_f32_16x16x32_bf16 v[4:7], v[210:213], v[182:185], v[4:7]
	v_mfma_f32_16x16x32_bf16 v[32:35], v[202:205], v[190:193], v[32:35]
	v_mfma_f32_16x16x32_bf16 v[0:3], v[210:213], v[190:193], v[0:3]
	s_setprio 1
	s_add_i32 s59, s59, 2
	s_add_u32 vcc_lo, vcc_lo, 0x100
	s_addc_u32 vcc_hi, vcc_hi, 0
	s_add_u32 s55, s55, 0x100
	s_addc_u32 s57, s57, 0
	s_cmp_gt_u32 s59, 13
	s_barrier
	s_cbranch_scc0 .LBB0_703
	v_lshl_add_u32 v164, s84, 8, v231
	v_lshl_add_u64 v[44:45], v[164:165], 2, s[34:35]
	global_load_dword v184, v[44:45], off
	v_or_b32_e32 v182, 16, v164
	v_mov_b32_e32 v183, v165
	v_lshl_add_u64 v[44:45], v[182:183], 2, s[34:35]
	global_load_dword v186, v[44:45], off
	v_or_b32_e32 v44, 32, v164
	v_mov_b32_e32 v45, v165
	v_lshl_add_u64 v[44:45], v[44:45], 2, s[34:35]
	v_or_b32_e32 v180, 48, v164
	v_mov_b32_e32 v181, v165
	global_load_dword v200, v[44:45], off
	v_lshl_add_u64 v[44:45], v[180:181], 2, s[34:35]
	v_add_u32_e32 v178, 0x80, v164
	v_mov_b32_e32 v179, v165
	global_load_dword v185, v[44:45], off
	v_lshl_add_u64 v[44:45], v[178:179], 2, s[34:35]
	v_add_u32_e32 v174, 0x90, v164
	v_mov_b32_e32 v175, v165
	global_load_dword v183, v[44:45], off
	v_lshl_add_u64 v[44:45], v[174:175], 2, s[34:35]
	global_load_dword v181, v[44:45], off
	v_add_u32_e32 v44, 0xa0, v164
	v_mov_b32_e32 v45, v165
	v_lshl_add_u64 v[44:45], v[44:45], 2, s[34:35]
	global_load_dword v175, v[44:45], off
	v_add_u32_e32 v44, 0xb0, v164
	v_mov_b32_e32 v45, v165
	v_lshl_or_b32 v176, s88, 7, v235
	v_lshl_add_u64 v[44:45], v[44:45], 2, s[34:35]
	v_ashrrev_i32_e32 v177, 31, v176
	v_readlane_b32 s44, v254, 1
	global_load_dword v179, v[44:45], off
	v_lshlrev_b64 v[44:45], 2, v[176:177]
	v_readlane_b32 s48, v254, 5
	v_readlane_b32 s49, v254, 6
	v_readlane_b32 s50, v254, 7
	v_readlane_b32 s51, v254, 8
	v_lshl_add_u64 v[48:49], s[48:49], 0, v[44:45]
	v_lshl_add_u64 v[52:53], s[96:97], 0, v[44:45]
	v_lshl_add_u64 v[56:57], s[86:87], 0, v[44:45]
	v_lshl_add_u64 v[80:81], s[50:51], 0, v[44:45]
	global_load_dwordx4 v[44:47], v[48:49], off offset:16
	global_load_dwordx4 v[68:71], v[48:49], off
	s_nop 0
	global_load_dwordx4 v[48:51], v[52:53], off offset:16
	global_load_dwordx4 v[72:75], v[52:53], off
	s_nop 0
	global_load_dwordx4 v[52:55], v[56:57], off offset:16
	global_load_dwordx4 v[76:79], v[56:57], off
	s_nop 0
	global_load_dwordx4 v[56:59], v[80:81], off offset:16
	s_nop 0
	global_load_dwordx4 v[80:83], v[80:81], off
	v_mov_b32_e32 v190, 0
	v_mov_b32_e32 v192, 0
	v_mov_b32_e32 v191, 0
	v_mov_b32_e32 v193, 0
	v_mov_b32_e32 v196, 0
	s_lshl_b32 s3, s84, 2
	v_mov_b32_e32 v198, 0
	s_add_i32 s3, s3, s10
	v_mov_b32_e32 v197, 0
	s_mul_i32 s51, s3, 6
	v_mov_b32_e32 v199, 0
	v_readlane_b32 s45, v254, 2
	v_readlane_b32 s46, v254, 3
	v_readlane_b32 s47, v254, 4
	s_waitcnt vmcnt(0)
	v_fmamk_f32 v177, v184, 0x3a800000, v239
	v_cmp_gt_f32_e32 vcc, s33, v177
	v_mul_f32_e32 v184, 0x4b800000, v177
	s_nop 0
	v_cndmask_b32_e32 v177, v177, v184, vcc
	v_rsq_f32_e32 v177, v177
	s_nop 0
	v_mul_f32_e32 v184, 0x45800000, v177
	v_cndmask_b32_e32 v188, v177, v184, vcc
	v_fmamk_f32 v177, v186, 0x3a800000, v239
	v_cmp_gt_f32_e32 vcc, s33, v177
	v_mul_f32_e32 v184, 0x4b800000, v177
	v_pk_mul_f32 v[186:187], v[156:157], v[188:189] op_sel_hi:[1,0]
	v_cndmask_b32_e32 v177, v177, v184, vcc
	v_rsq_f32_e32 v177, v177
	v_cndmask_b32_e64 v156, v186, 0, s[38:39]
	v_pk_mul_f32 v[194:195], v[158:159], v[188:189] op_sel_hi:[1,0]
	v_mul_f32_e32 v184, 0x45800000, v177
	v_cndmask_b32_e32 v184, v177, v184, vcc
	v_mov_b32_dpp v190, v156 row_ror:1 row_mask:0xf bank_mask:0xf
	v_pk_mul_f32 v[156:157], v[152:153], v[184:185] op_sel_hi:[1,0]
	v_pk_mul_f32 v[158:159], v[154:155], v[184:185] op_sel_hi:[1,0]
	v_cndmask_b32_e64 v152, v186, v156, s[42:43]
	v_add_u32_e32 v155, s51, v234
	s_nop 0
	v_mov_b32_dpp v192, v152 row_ror:15 row_mask:0xf bank_mask:0xf
	v_cndmask_b32_e64 v152, v187, 0, s[38:39]
	s_nop 1
	v_mov_b32_dpp v191, v152 row_ror:1 row_mask:0xf bank_mask:0xf
	v_cndmask_b32_e64 v152, v187, v157, s[42:43]
	s_nop 1
	v_mov_b32_dpp v193, v152 row_ror:15 row_mask:0xf bank_mask:0xf
	v_cndmask_b32_e64 v152, v194, 0, s[38:39]
	s_nop 1
	v_mov_b32_dpp v196, v152 row_ror:1 row_mask:0xf bank_mask:0xf
	v_cndmask_b32_e64 v152, v194, v158, s[42:43]
	s_nop 1
	v_mov_b32_dpp v198, v152 row_ror:15 row_mask:0xf bank_mask:0xf
	v_cndmask_b32_e64 v152, v195, 0, s[38:39]
	s_nop 1
	v_mov_b32_dpp v197, v152 row_ror:1 row_mask:0xf bank_mask:0xf
	v_cndmask_b32_e64 v152, v195, v159, s[42:43]
	s_nop 1
	v_mov_b32_dpp v199, v152 row_ror:15 row_mask:0xf bank_mask:0xf
	s_and_saveexec_b64 s[0:1], s[70:71]
	s_cbranch_execz .LBB0_706
	v_mad_u64_u32 v[202:203], s[22:23], v155, s65, v[176:177]
	v_mov_b32_e32 v203, v165
	v_cvt_pk_bf16_f32 v152, v186, v187
	v_cvt_pk_bf16_f32 v153, v194, v195
	v_lshl_add_u64 v[202:203], v[202:203], 1, s[30:31]
	global_store_dwordx2 v[202:203], v[152:153], off

.LBB0_888:
	ds_read_b128 v[140:143], v149
	ds_read_b128 v[152:155], v149 offset:1024
	ds_read_b128 v[156:159], v149 offset:2048
	ds_read_b128 v[160:163], v149 offset:3072
	s_add_u32 s10, s2, 0x100
	s_addc_u32 s11, s3, 0
	s_cmp_eq_u32 s39, 40
	s_cselect_b32 s15, s7, s11
	s_cselect_b32 s14, s6, s10
	s_cselect_b32 s13, s5, s38
	s_cselect_b32 s12, s4, s37
	v_lshl_add_u64 v[144:145], s[2:3], 0, v[132:133]
	s_add_i32 m0, s23, 0xc000
	ds_read_b128 v[164:167], v150
	ds_read_b128 v[168:171], v150 offset:1024
	ds_read_b128 v[172:175], v150 offset:2048
	ds_read_b128 v[176:179], v150 offset:3072
	ds_read_b128 v[180:183], v150 offset:4096
	ds_read_b128 v[184:187], v150 offset:5120
	ds_read_b128 v[188:191], v150 offset:6144
	ds_read_b128 v[192:195], v150 offset:7168
	global_load_lds_dwordx4 v[144:145], off
	v_lshl_add_u64 v[144:145], s[2:3], 0, v[134:135]
	s_add_i32 m0, s23, 0xe000
	s_nop 0
	global_load_lds_dwordx4 v[144:145], off
	s_waitcnt lgkmcnt(8)
	s_barrier
	s_waitcnt lgkmcnt(0)
	s_setprio 0
	s_waitcnt lgkmcnt(0)
	v_mfma_f32_16x16x32_bf16 v[124:127], v[140:143], v[164:167], v[124:127]
	v_mfma_f32_16x16x32_bf16 v[120:123], v[156:159], v[164:167], v[120:123]
	v_mfma_f32_16x16x32_bf16 v[116:119], v[140:143], v[172:175], v[116:119]
	v_mfma_f32_16x16x32_bf16 v[112:115], v[156:159], v[172:175], v[112:115]
	v_mfma_f32_16x16x32_bf16 v[92:95], v[140:143], v[180:183], v[92:95]
	v_mfma_f32_16x16x32_bf16 v[88:91], v[156:159], v[180:183], v[88:91]
	v_mfma_f32_16x16x32_bf16 v[84:87], v[140:143], v[188:191], v[84:87]
	v_mfma_f32_16x16x32_bf16 v[80:83], v[156:159], v[188:191], v[80:83]
	v_mfma_f32_16x16x32_bf16 v[124:127], v[152:155], v[168:171], v[124:127]
	v_mfma_f32_16x16x32_bf16 v[120:123], v[160:163], v[168:171], v[120:123]
	v_mfma_f32_16x16x32_bf16 v[116:119], v[152:155], v[176:179], v[116:119]
	v_mfma_f32_16x16x32_bf16 v[112:115], v[160:163], v[176:179], v[112:115]
	v_mfma_f32_16x16x32_bf16 v[92:95], v[152:155], v[184:187], v[92:95]
	v_mfma_f32_16x16x32_bf16 v[88:91], v[160:163], v[184:187], v[88:91]
	v_mfma_f32_16x16x32_bf16 v[84:87], v[152:155], v[192:195], v[84:87]
	v_mfma_f32_16x16x32_bf16 v[80:83], v[160:163], v[192:195], v[80:83]
	s_setprio 1
	s_barrier
	s_add_i32 s2, s30, s22
	v_lshl_add_u64 v[144:145], s[12:13], 0, v[128:129]
	s_mov_b32 m0, s2
	ds_read_b128 v[196:199], v151
	ds_read_b128 v[200:203], v151 offset:1024
	ds_read_b128 v[204:207], v151 offset:2048
	ds_read_b128 v[208:211], v151 offset:3072
	global_load_lds_dwordx4 v[144:145], off
	v_lshl_add_u64 v[212:213], s[12:13], 0, v[130:131]
	s_add_i32 m0, s2, 0x2000
	s_nop 0
	global_load_lds_dwordx4 v[212:213], off
	s_barrier
	s_waitcnt lgkmcnt(0)
	s_setprio 0
	s_waitcnt lgkmcnt(0)
	v_mfma_f32_16x16x32_bf16 v[108:111], v[196:199], v[164:167], v[108:111]
	v_mfma_f32_16x16x32_bf16 v[104:107], v[204:207], v[164:167], v[104:107]
	v_mfma_f32_16x16x32_bf16 v[100:103], v[196:199], v[172:175], v[100:103]
	v_mfma_f32_16x16x32_bf16 v[96:99], v[204:207], v[172:175], v[96:99]
	v_mfma_f32_16x16x32_bf16 v[76:79], v[196:199], v[180:183], v[76:79]
	v_mfma_f32_16x16x32_bf16 v[72:75], v[204:207], v[180:183], v[72:75]
	v_mfma_f32_16x16x32_bf16 v[68:71], v[196:199], v[188:191], v[68:71]
	v_mfma_f32_16x16x32_bf16 v[64:67], v[204:207], v[188:191], v[64:67]
	v_mfma_f32_16x16x32_bf16 v[108:111], v[200:203], v[168:171], v[108:111]
	v_mfma_f32_16x16x32_bf16 v[104:107], v[208:211], v[168:171], v[104:107]
	v_mfma_f32_16x16x32_bf16 v[100:103], v[200:203], v[176:179], v[100:103]
	v_mfma_f32_16x16x32_bf16 v[96:99], v[208:211], v[176:179], v[96:99]
	v_mfma_f32_16x16x32_bf16 v[76:79], v[200:203], v[184:187], v[76:79]
	v_mfma_f32_16x16x32_bf16 v[72:75], v[208:211], v[184:187], v[72:75]
	v_mfma_f32_16x16x32_bf16 v[68:71], v[200:203], v[192:195], v[68:71]
	v_mfma_f32_16x16x32_bf16 v[64:67], v[208:211], v[192:195], v[64:67]
	s_setprio 1
	s_mov_b32 m0, s23
	v_lshl_add_u64 v[214:215], s[14:15], 0, v[128:129]
	s_barrier
	ds_read_b128 v[164:167], v150 offset:16384
	ds_read_b128 v[168:171], v150 offset:17408
	ds_read_b128 v[172:175], v150 offset:18432
	ds_read_b128 v[176:179], v150 offset:19456
	ds_read_b128 v[180:183], v150 offset:20480
	ds_read_b128 v[184:187], v150 offset:21504
	ds_read_b128 v[188:191], v150 offset:22528
	ds_read_b128 v[192:195], v150 offset:23552
	global_load_lds_dwordx4 v[214:215], off
	v_lshl_add_u64 v[216:217], s[14:15], 0, v[130:131]
	s_mov_b32 m0, s24
	s_nop 0
	global_load_lds_dwordx4 v[216:217], off
	s_barrier
	s_waitcnt lgkmcnt(0)
	s_setprio 0
	s_waitcnt lgkmcnt(0)
	v_mfma_f32_16x16x32_bf16 v[60:63], v[140:143], v[164:167], v[60:63]
	v_mfma_f32_16x16x32_bf16 v[56:59], v[156:159], v[164:167], v[56:59]
	v_mfma_f32_16x16x32_bf16 v[52:55], v[140:143], v[172:175], v[52:55]
	v_mfma_f32_16x16x32_bf16 v[48:51], v[156:159], v[172:175], v[48:51]
	v_mfma_f32_16x16x32_bf16 v[28:31], v[140:143], v[180:183], v[28:31]
	v_mfma_f32_16x16x32_bf16 v[24:27], v[156:159], v[180:183], v[24:27]
	v_mfma_f32_16x16x32_bf16 v[16:19], v[140:143], v[188:191], v[16:19]
	v_mfma_f32_16x16x32_bf16 v[8:11], v[156:159], v[188:191], v[8:11]
	v_mfma_f32_16x16x32_bf16 v[60:63], v[152:155], v[168:171], v[60:63]
	v_mfma_f32_16x16x32_bf16 v[56:59], v[160:163], v[168:171], v[56:59]
	v_mfma_f32_16x16x32_bf16 v[52:55], v[152:155], v[176:179], v[52:55]
	v_mfma_f32_16x16x32_bf16 v[48:51], v[160:163], v[176:179], v[48:51]
	v_mfma_f32_16x16x32_bf16 v[28:31], v[152:155], v[184:187], v[28:31]
	v_mfma_f32_16x16x32_bf16 v[24:27], v[160:163], v[184:187], v[24:27]
	v_mfma_f32_16x16x32_bf16 v[16:19], v[152:155], v[192:195], v[16:19]
	v_mfma_f32_16x16x32_bf16 v[8:11], v[160:163], v[192:195], v[8:11]
	s_setprio 1
	s_barrier
	s_add_u32 s2, s12, 0xb0000
	s_addc_u32 s3, s13, 0
	s_add_i32 s40, s31, s22
	v_lshl_add_u64 v[140:141], s[2:3], 0, v[128:129]
	s_mov_b32 m0, s40
	s_nop 0
	global_load_lds_dwordx4 v[140:141], off
	v_lshl_add_u64 v[140:141], s[2:3], 0, v[130:131]
	s_add_i32 m0, s40, 0x2000
	s_nop 0
	global_load_lds_dwordx4 v[140:141], off
	s_waitcnt vmcnt(6)
	s_barrier
	s_setprio 0
	v_mfma_f32_16x16x32_bf16 v[44:47], v[196:199], v[164:167], v[44:47]
	v_mfma_f32_16x16x32_bf16 v[40:43], v[204:207], v[164:167], v[40:43]
	v_mfma_f32_16x16x32_bf16 v[36:39], v[196:199], v[172:175], v[36:39]
	v_mfma_f32_16x16x32_bf16 v[32:35], v[204:207], v[172:175], v[32:35]
	v_mfma_f32_16x16x32_bf16 v[20:23], v[196:199], v[180:183], v[20:23]
	v_mfma_f32_16x16x32_bf16 v[12:15], v[204:207], v[180:183], v[12:15]
	v_mfma_f32_16x16x32_bf16 v[4:7], v[196:199], v[188:191], v[4:7]
	v_mfma_f32_16x16x32_bf16 v[0:3], v[204:207], v[188:191], v[0:3]
	v_mfma_f32_16x16x32_bf16 v[44:47], v[200:203], v[168:171], v[44:47]
	v_mfma_f32_16x16x32_bf16 v[40:43], v[208:211], v[168:171], v[40:43]
	v_mfma_f32_16x16x32_bf16 v[36:39], v[200:203], v[176:179], v[36:39]
	v_mfma_f32_16x16x32_bf16 v[32:35], v[208:211], v[176:179], v[32:35]
	v_mfma_f32_16x16x32_bf16 v[20:23], v[200:203], v[184:187], v[20:23]
	v_mfma_f32_16x16x32_bf16 v[12:15], v[208:211], v[184:187], v[12:15]
	v_mfma_f32_16x16x32_bf16 v[4:7], v[200:203], v[192:195], v[4:7]
	v_mfma_f32_16x16x32_bf16 v[0:3], v[208:211], v[192:195], v[0:3]
	s_setprio 1
	s_add_i32 s40, 0, 0x18000
	v_add_u32_e32 v160, s40, v147
	s_barrier
	ds_read_b128 v[140:143], v160
	ds_read_b128 v[152:155], v160 offset:1024
	ds_read_b128 v[156:159], v160 offset:2048
	ds_read_b128 v[160:163], v160 offset:3072
	s_add_u32 s2, s14, 0xb0000
	s_addc_u32 s3, s15, 0
	s_mov_b32 m0, s25
	v_lshl_add_u64 v[196:197], s[2:3], 0, v[128:129]
	ds_read_b128 v[164:167], v150 offset:32768
	ds_read_b128 v[168:171], v150 offset:33792
	ds_read_b128 v[172:175], v150 offset:34816
	ds_read_b128 v[176:179], v150 offset:35840
	ds_read_b128 v[180:183], v150 offset:36864
	ds_read_b128 v[184:187], v150 offset:37888
	ds_read_b128 v[188:191], v150 offset:38912
	ds_read_b128 v[192:195], v150 offset:39936
	global_load_lds_dwordx4 v[196:197], off
	v_lshl_add_u64 v[196:197], s[2:3], 0, v[130:131]
	s_mov_b32 m0, s26
	s_nop 0
	global_load_lds_dwordx4 v[196:197], off
	s_waitcnt lgkmcnt(8)
	s_barrier
	s_waitcnt lgkmcnt(0)
	s_setprio 0
	s_waitcnt lgkmcnt(0)
	v_mfma_f32_16x16x32_bf16 v[124:127], v[140:143], v[164:167], v[124:127]
	v_mfma_f32_16x16x32_bf16 v[120:123], v[156:159], v[164:167], v[120:123]
	v_mfma_f32_16x16x32_bf16 v[116:119], v[140:143], v[172:175], v[116:119]
	v_mfma_f32_16x16x32_bf16 v[112:115], v[156:159], v[172:175], v[112:115]
	v_mfma_f32_16x16x32_bf16 v[92:95], v[140:143], v[180:183], v[92:95]
	v_mfma_f32_16x16x32_bf16 v[88:91], v[156:159], v[180:183], v[88:91]
	v_mfma_f32_16x16x32_bf16 v[84:87], v[140:143], v[188:191], v[84:87]
	v_mfma_f32_16x16x32_bf16 v[80:83], v[156:159], v[188:191], v[80:83]
	v_mfma_f32_16x16x32_bf16 v[124:127], v[152:155], v[168:171], v[124:127]
	v_mfma_f32_16x16x32_bf16 v[120:123], v[160:163], v[168:171], v[120:123]
	v_mfma_f32_16x16x32_bf16 v[116:119], v[152:155], v[176:179], v[116:119]
	v_mfma_f32_16x16x32_bf16 v[112:115], v[160:163], v[176:179], v[112:115]
	v_mfma_f32_16x16x32_bf16 v[92:95], v[152:155], v[184:187], v[92:95]
	v_mfma_f32_16x16x32_bf16 v[88:91], v[160:163], v[184:187], v[88:91]
	v_mfma_f32_16x16x32_bf16 v[84:87], v[152:155], v[192:195], v[84:87]
	v_mfma_f32_16x16x32_bf16 v[80:83], v[160:163], v[192:195], v[80:83]
	s_setprio 1
	s_barrier
	s_add_i32 s14, 0, 0x1c000
	s_add_i32 s2, s40, s22
	v_add_u32_e32 v208, s14, v147
	v_lshl_add_u64 v[144:145], v[144:145], 0, s[8:9]
	s_mov_b32 m0, s2
	ds_read_b128 v[196:199], v208
	ds_read_b128 v[200:203], v208 offset:1024
	ds_read_b128 v[204:207], v208 offset:2048
	ds_read_b128 v[208:211], v208 offset:3072
	global_load_lds_dwordx4 v[144:145], off
	v_lshl_add_u64 v[144:145], v[212:213], 0, s[8:9]
	s_add_i32 m0, s2, 0x2000
	s_nop 0
	global_load_lds_dwordx4 v[144:145], off
	s_barrier
	s_waitcnt lgkmcnt(0)
	s_setprio 0
	s_waitcnt lgkmcnt(0)
	v_mfma_f32_16x16x32_bf16 v[108:111], v[196:199], v[164:167], v[108:111]
	v_mfma_f32_16x16x32_bf16 v[104:107], v[204:207], v[164:167], v[104:107]
	v_mfma_f32_16x16x32_bf16 v[100:103], v[196:199], v[172:175], v[100:103]
	v_mfma_f32_16x16x32_bf16 v[96:99], v[204:207], v[172:175], v[96:99]
	v_mfma_f32_16x16x32_bf16 v[76:79], v[196:199], v[180:183], v[76:79]
	v_mfma_f32_16x16x32_bf16 v[72:75], v[204:207], v[180:183], v[72:75]
	v_mfma_f32_16x16x32_bf16 v[68:71], v[196:199], v[188:191], v[68:71]
	v_mfma_f32_16x16x32_bf16 v[64:67], v[204:207], v[188:191], v[64:67]
	v_mfma_f32_16x16x32_bf16 v[108:111], v[200:203], v[168:171], v[108:111]
	v_mfma_f32_16x16x32_bf16 v[104:107], v[208:211], v[168:171], v[104:107]
	v_mfma_f32_16x16x32_bf16 v[100:103], v[200:203], v[176:179], v[100:103]
	v_mfma_f32_16x16x32_bf16 v[96:99], v[208:211], v[176:179], v[96:99]
	v_mfma_f32_16x16x32_bf16 v[76:79], v[200:203], v[184:187], v[76:79]
	v_mfma_f32_16x16x32_bf16 v[72:75], v[208:211], v[184:187], v[72:75]
	v_mfma_f32_16x16x32_bf16 v[68:71], v[200:203], v[192:195], v[68:71]
	v_mfma_f32_16x16x32_bf16 v[64:67], v[208:211], v[192:195], v[64:67]
	s_setprio 1
	s_mov_b32 m0, s28
	v_lshl_add_u64 v[144:145], v[214:215], 0, s[8:9]
	s_barrier
	ds_read_b128 v[164:167], v150 offset:49152
	ds_read_b128 v[168:171], v150 offset:50176
	ds_read_b128 v[172:175], v150 offset:51200
	ds_read_b128 v[176:179], v150 offset:52224
	ds_read_b128 v[180:183], v150 offset:53248
	ds_read_b128 v[184:187], v150 offset:54272
	ds_read_b128 v[188:191], v150 offset:55296
	ds_read_b128 v[192:195], v150 offset:56320
	global_load_lds_dwordx4 v[144:145], off
	v_lshl_add_u64 v[144:145], v[216:217], 0, s[8:9]
	s_mov_b32 m0, s29
	s_nop 0
	global_load_lds_dwordx4 v[144:145], off
	s_barrier
	s_waitcnt lgkmcnt(0)
	s_setprio 0
	s_waitcnt lgkmcnt(0)
	v_mfma_f32_16x16x32_bf16 v[60:63], v[140:143], v[164:167], v[60:63]
	v_mfma_f32_16x16x32_bf16 v[56:59], v[156:159], v[164:167], v[56:59]
	v_mfma_f32_16x16x32_bf16 v[52:55], v[140:143], v[172:175], v[52:55]
	v_mfma_f32_16x16x32_bf16 v[48:51], v[156:159], v[172:175], v[48:51]
	v_mfma_f32_16x16x32_bf16 v[28:31], v[140:143], v[180:183], v[28:31]
	v_mfma_f32_16x16x32_bf16 v[24:27], v[156:159], v[180:183], v[24:27]
	v_mfma_f32_16x16x32_bf16 v[16:19], v[140:143], v[188:191], v[16:19]
	v_mfma_f32_16x16x32_bf16 v[8:11], v[156:159], v[188:191], v[8:11]
	v_mfma_f32_16x16x32_bf16 v[60:63], v[152:155], v[168:171], v[60:63]
	v_mfma_f32_16x16x32_bf16 v[56:59], v[160:163], v[168:171], v[56:59]
	v_mfma_f32_16x16x32_bf16 v[52:55], v[152:155], v[176:179], v[52:55]
	v_mfma_f32_16x16x32_bf16 v[48:51], v[160:163], v[176:179], v[48:51]
	v_mfma_f32_16x16x32_bf16 v[28:31], v[152:155], v[184:187], v[28:31]
	v_mfma_f32_16x16x32_bf16 v[24:27], v[160:163], v[184:187], v[24:27]
	v_mfma_f32_16x16x32_bf16 v[16:19], v[152:155], v[192:195], v[16:19]
	v_mfma_f32_16x16x32_bf16 v[8:11], v[160:163], v[192:195], v[8:11]
	s_setprio 1
	s_barrier
	s_add_u32 s2, s12, 0xb0080
	s_addc_u32 s3, s13, 0
	s_add_i32 s12, s14, s22
	v_lshl_add_u64 v[140:141], s[2:3], 0, v[128:129]
	s_mov_b32 m0, s12
	s_nop 0
	global_load_lds_dwordx4 v[140:141], off
	v_lshl_add_u64 v[140:141], s[2:3], 0, v[130:131]
	s_add_i32 m0, s12, 0x2000
	s_nop 0
	global_load_lds_dwordx4 v[140:141], off
	s_waitcnt vmcnt(6)
	s_barrier
	s_setprio 0
	v_mfma_f32_16x16x32_bf16 v[44:47], v[196:199], v[164:167], v[44:47]
	v_mfma_f32_16x16x32_bf16 v[40:43], v[204:207], v[164:167], v[40:43]
	v_mfma_f32_16x16x32_bf16 v[36:39], v[196:199], v[172:175], v[36:39]
	v_mfma_f32_16x16x32_bf16 v[32:35], v[204:207], v[172:175], v[32:35]
	v_mfma_f32_16x16x32_bf16 v[20:23], v[196:199], v[180:183], v[20:23]
	v_mfma_f32_16x16x32_bf16 v[12:15], v[204:207], v[180:183], v[12:15]
	v_mfma_f32_16x16x32_bf16 v[4:7], v[196:199], v[188:191], v[4:7]
	v_mfma_f32_16x16x32_bf16 v[0:3], v[204:207], v[188:191], v[0:3]
	v_mfma_f32_16x16x32_bf16 v[44:47], v[200:203], v[168:171], v[44:47]
	v_mfma_f32_16x16x32_bf16 v[40:43], v[208:211], v[168:171], v[40:43]
	v_mfma_f32_16x16x32_bf16 v[36:39], v[200:203], v[176:179], v[36:39]
	v_mfma_f32_16x16x32_bf16 v[32:35], v[208:211], v[176:179], v[32:35]
	v_mfma_f32_16x16x32_bf16 v[20:23], v[200:203], v[184:187], v[20:23]
	v_mfma_f32_16x16x32_bf16 v[12:15], v[208:211], v[184:187], v[12:15]
	v_mfma_f32_16x16x32_bf16 v[4:7], v[200:203], v[192:195], v[4:7]
	v_mfma_f32_16x16x32_bf16 v[0:3], v[208:211], v[192:195], v[0:3]
	s_setprio 1
	s_add_i32 s39, s39, 2
	s_add_u32 s37, s37, 0x100
	s_addc_u32 s38, s38, 0
	s_cmp_gt_u32 s39, 41
	s_mov_b64 s[2:3], s[10:11]
	s_barrier
	s_cbranch_scc0 .LBB0_888
	v_lshl_or_b32 v140, s36, 8, v148
	v_lshl_add_u32 v144, s35, 8, v146
	v_ashrrev_i32_e32 v141, 31, v140
	v_lshlrev_b64 v[140:141], 2, v[140:141]
	v_ashrrev_i32_e32 v145, 31, v144
	v_lshl_add_u64 v[142:143], s[78:79], 0, v[140:141]
	v_lshlrev_b64 v[184:185], 12, v[144:145]
	v_lshl_add_u64 v[164:165], v[142:143], 0, v[184:185]
	v_or_b32_e32 v168, 16, v144
	global_load_dwordx4 v[152:155], v[164:165], off offset:16
	global_load_dwordx4 v[156:159], v[164:165], off
	global_load_dwordx4 v[160:163], v[164:165], off offset:144
	s_nop 0
	global_load_dwordx4 v[164:167], v[164:165], off offset:128
	v_ashrrev_i32_e32 v169, 31, v168
	v_lshlrev_b64 v[186:187], 12, v[168:169]
	v_lshl_add_u64 v[180:181], v[142:143], 0, v[186:187]
	global_load_dwordx4 v[168:171], v[180:181], off offset:16
	global_load_dwordx4 v[172:175], v[180:181], off
	global_load_dwordx4 v[176:179], v[180:181], off offset:144
	s_nop 0
	global_load_dwordx4 v[180:183], v[180:181], off offset:128
	s_and_b64 vcc, exec, s[0:1]
	s_mov_b32 s36, s34
	s_mov_b32 s35, s33
	s_mov_b64 s[10:11], s[4:5]
	s_mov_b64 s[2:3], s[6:7]
	s_waitcnt vmcnt(0)
	v_pk_add_f32 v[120:121], v[120:121], v[152:153]
	v_lshl_add_u64 v[152:153], s[78:79], 0, v[184:185]
	v_pk_add_f32 v[126:127], v[126:127], v[158:159]
	v_pk_add_f32 v[124:125], v[124:125], v[156:157]
	v_pk_add_f32 v[108:109], v[108:109], v[164:165]
	v_lshl_add_u64 v[152:153], v[152:153], 0, v[140:141]
	v_pk_add_f32 v[122:123], v[122:123], v[154:155]
	v_pk_add_f32 v[110:111], v[110:111], v[166:167]
	v_pk_add_f32 v[106:107], v[106:107], v[162:163]
	v_pk_add_f32 v[104:105], v[104:105], v[160:161]
	global_store_dwordx4 v[152:153], v[124:127], off nt
	global_store_dwordx4 v[152:153], v[120:123], off offset:16 nt
	global_store_dwordx4 v[152:153], v[108:111], off offset:128 nt
	global_store_dwordx4 v[152:153], v[104:107], off offset:144 nt
	v_pk_add_f32 v[96:97], v[96:97], v[176:177]
	v_pk_add_f32 v[108:109], v[112:113], v[168:169]
	v_lshl_add_u64 v[112:113], s[78:79], 0, v[186:187]
	v_pk_add_f32 v[106:107], v[118:119], v[174:175]
	v_pk_add_f32 v[104:105], v[116:117], v[172:173]
	v_lshl_add_u64 v[112:113], v[112:113], 0, v[140:141]
	v_pk_add_f32 v[110:111], v[114:115], v[170:171]
	v_pk_add_f32 v[102:103], v[102:103], v[182:183]
	v_pk_add_f32 v[100:101], v[100:101], v[180:181]
	v_pk_add_f32 v[98:99], v[98:99], v[178:179]
	global_store_dwordx4 v[112:113], v[104:107], off nt
	global_store_dwordx4 v[112:113], v[108:111], off offset:16 nt
	global_store_dwordx4 v[112:113], v[100:103], off offset:128 nt
	global_store_dwordx4 v[112:113], v[96:99], off offset:144 nt
	v_or_b32_e32 v112, 48, v144
	v_ashrrev_i32_e32 v113, 31, v112
	v_or_b32_e32 v96, 32, v144
	v_ashrrev_i32_e32 v97, 31, v96
	v_lshlrev_b64 v[152:153], 12, v[96:97]
	v_lshl_add_u64 v[108:109], v[142:143], 0, v[152:153]
	global_load_dwordx4 v[96:99], v[108:109], off offset:16
	global_load_dwordx4 v[100:103], v[108:109], off
	global_load_dwordx4 v[104:107], v[108:109], off offset:144
	s_nop 0
	global_load_dwordx4 v[108:111], v[108:109], off offset:128
	v_lshlrev_b64 v[154:155], 12, v[112:113]
	v_lshl_add_u64 v[124:125], v[142:143], 0, v[154:155]
	global_load_dwordx4 v[112:115], v[124:125], off offset:16
	global_load_dwordx4 v[116:119], v[124:125], off
	global_load_dwordx4 v[120:123], v[124:125], off offset:144
	s_nop 0
	global_load_dwordx4 v[124:127], v[124:125], off offset:128
	s_waitcnt vmcnt(0)
	v_pk_add_f32 v[88:89], v[88:89], v[96:97]
	v_lshl_add_u64 v[96:97], s[78:79], 0, v[152:153]
	v_pk_add_f32 v[94:95], v[94:95], v[102:103]
	v_pk_add_f32 v[92:93], v[92:93], v[100:101]
	v_pk_add_f32 v[76:77], v[76:77], v[108:109]
	v_lshl_add_u64 v[96:97], v[96:97], 0, v[140:141]
	v_pk_add_f32 v[90:91], v[90:91], v[98:99]
	v_pk_add_f32 v[78:79], v[78:79], v[110:111]
	v_pk_add_f32 v[74:75], v[74:75], v[106:107]
	v_pk_add_f32 v[72:73], v[72:73], v[104:105]
	global_store_dwordx4 v[96:97], v[92:95], off nt
	global_store_dwordx4 v[96:97], v[88:91], off offset:16 nt
	global_store_dwordx4 v[96:97], v[76:79], off offset:128 nt
	global_store_dwordx4 v[96:97], v[72:75], off offset:144 nt
	v_pk_add_f32 v[64:65], v[64:65], v[120:121]
	v_pk_add_f32 v[76:77], v[80:81], v[112:113]
	v_lshl_add_u64 v[80:81], s[78:79], 0, v[154:155]
	v_pk_add_f32 v[74:75], v[86:87], v[118:119]
	v_pk_add_f32 v[72:73], v[84:85], v[116:117]
	v_lshl_add_u64 v[80:81], v[80:81], 0, v[140:141]
	v_pk_add_f32 v[78:79], v[82:83], v[114:115]
	v_pk_add_f32 v[70:71], v[70:71], v[126:127]
	v_pk_add_f32 v[68:69], v[68:69], v[124:125]
	v_pk_add_f32 v[66:67], v[66:67], v[122:123]
	global_store_dwordx4 v[80:81], v[72:75], off nt
	global_store_dwordx4 v[80:81], v[76:79], off offset:16 nt
	global_store_dwordx4 v[80:81], v[68:71], off offset:128 nt
	global_store_dwordx4 v[80:81], v[64:67], off offset:144 nt
	s_nop 1
	v_add_u32_e32 v64, 0x80, v144
	v_ashrrev_i32_e32 v65, 31, v64
	v_lshlrev_b64 v[96:97], 12, v[64:65]
	v_lshl_add_u64 v[80:81], v[142:143], 0, v[96:97]
	global_load_dwordx4 v[64:67], v[80:81], off offset:16
	global_load_dwordx4 v[68:71], v[80:81], off
	global_load_dwordx4 v[72:75], v[80:81], off offset:144
	global_load_dwordx4 v[76:79], v[80:81], off offset:128
	v_add_u32_e32 v80, 0x90, v144
	v_ashrrev_i32_e32 v81, 31, v80
	v_lshlrev_b64 v[98:99], 12, v[80:81]
	v_lshl_add_u64 v[100:101], v[142:143], 0, v[98:99]
	global_load_dwordx4 v[80:83], v[100:101], off offset:16
	global_load_dwordx4 v[84:87], v[100:101], off
	global_load_dwordx4 v[88:91], v[100:101], off offset:144
	global_load_dwordx4 v[92:95], v[100:101], off offset:128
	s_waitcnt vmcnt(0)
	v_pk_add_f32 v[56:57], v[56:57], v[64:65]
	v_lshl_add_u64 v[64:65], s[78:79], 0, v[96:97]
	v_pk_add_f32 v[62:63], v[62:63], v[70:71]
	v_pk_add_f32 v[60:61], v[60:61], v[68:69]
	v_pk_add_f32 v[44:45], v[44:45], v[76:77]
	v_lshl_add_u64 v[64:65], v[64:65], 0, v[140:141]
	v_pk_add_f32 v[58:59], v[58:59], v[66:67]
	v_pk_add_f32 v[46:47], v[46:47], v[78:79]
	v_pk_add_f32 v[42:43], v[42:43], v[74:75]
	v_pk_add_f32 v[40:41], v[40:41], v[72:73]
	global_store_dwordx4 v[64:65], v[60:63], off nt
	global_store_dwordx4 v[64:65], v[56:59], off offset:16 nt
	global_store_dwordx4 v[64:65], v[44:47], off offset:128 nt
	global_store_dwordx4 v[64:65], v[40:43], off offset:144 nt
	v_pk_add_f32 v[32:33], v[32:33], v[88:89]
	v_pk_add_f32 v[44:45], v[48:49], v[80:81]
	v_lshl_add_u64 v[48:49], s[78:79], 0, v[98:99]
	v_pk_add_f32 v[42:43], v[54:55], v[86:87]
	v_pk_add_f32 v[40:41], v[52:53], v[84:85]
	v_lshl_add_u64 v[48:49], v[48:49], 0, v[140:141]
	v_pk_add_f32 v[46:47], v[50:51], v[82:83]
	v_pk_add_f32 v[38:39], v[38:39], v[94:95]
	v_pk_add_f32 v[36:37], v[36:37], v[92:93]
	v_pk_add_f32 v[34:35], v[34:35], v[90:91]
	global_store_dwordx4 v[48:49], v[40:43], off nt
	global_store_dwordx4 v[48:49], v[44:47], off offset:16 nt
	global_store_dwordx4 v[48:49], v[36:39], off offset:128 nt
	global_store_dwordx4 v[48:49], v[32:35], off offset:144 nt
	s_nop 1
	v_add_u32_e32 v32, 0xa0, v144
	v_ashrrev_i32_e32 v33, 31, v32
	v_lshlrev_b64 v[60:61], 12, v[32:33]
	v_lshl_add_u64 v[48:49], v[142:143], 0, v[60:61]
	global_load_dwordx4 v[40:43], v[48:49], off offset:16
	global_load_dwordx4 v[44:47], v[48:49], off
	global_load_dwordx4 v[32:35], v[48:49], off offset:144
	global_load_dwordx4 v[36:39], v[48:49], off offset:128
	v_add_u32_e32 v48, 0xb0, v144
	v_ashrrev_i32_e32 v49, 31, v48
	v_lshlrev_b64 v[62:63], 12, v[48:49]
	v_lshl_add_u64 v[68:69], v[142:143], 0, v[62:63]
	global_load_dwordx4 v[48:51], v[68:69], off offset:16
	global_load_dwordx4 v[56:59], v[68:69], off
	global_load_dwordx4 v[52:55], v[68:69], off offset:144
	global_load_dwordx4 v[64:67], v[68:69], off offset:128
	s_waitcnt vmcnt(0)
	v_pk_add_f32 v[26:27], v[26:27], v[42:43]
	v_pk_add_f32 v[30:31], v[30:31], v[46:47]
	v_pk_add_f32 v[12:13], v[12:13], v[32:33]
	v_lshl_add_u64 v[32:33], s[78:79], 0, v[60:61]
	v_pk_add_f32 v[28:29], v[28:29], v[44:45]
	v_lshl_add_u64 v[32:33], v[32:33], 0, v[140:141]
	v_pk_add_f32 v[24:25], v[24:25], v[40:41]
	v_pk_add_f32 v[22:23], v[22:23], v[38:39]
	v_pk_add_f32 v[20:21], v[20:21], v[36:37]
	v_pk_add_f32 v[14:15], v[14:15], v[34:35]
	global_store_dwordx4 v[32:33], v[28:31], off nt
	global_store_dwordx4 v[32:33], v[24:27], off offset:16 nt
	global_store_dwordx4 v[32:33], v[20:23], off offset:128 nt
	global_store_dwordx4 v[32:33], v[12:15], off offset:144 nt
	v_pk_add_f32 v[10:11], v[10:11], v[50:51]
	v_pk_add_f32 v[8:9], v[8:9], v[48:49]
	v_pk_add_f32 v[12:13], v[16:17], v[56:57]
	v_lshl_add_u64 v[16:17], s[78:79], 0, v[62:63]
	v_pk_add_f32 v[14:15], v[18:19], v[58:59]
	v_lshl_add_u64 v[16:17], v[16:17], 0, v[140:141]
	v_pk_add_f32 v[6:7], v[6:7], v[66:67]
	v_pk_add_f32 v[4:5], v[4:5], v[64:65]
	v_pk_add_f32 v[2:3], v[2:3], v[54:55]
	v_pk_add_f32 v[0:1], v[0:1], v[52:53]
	global_store_dwordx4 v[16:17], v[12:15], off nt
	global_store_dwordx4 v[16:17], v[8:11], off offset:16 nt
	global_store_dwordx4 v[16:17], v[4:7], off offset:128 nt
	global_store_dwordx4 v[16:17], v[0:3], off offset:144 nt
	s_cbranch_vccz .LBB0_877
	s_waitcnt vmcnt(0)
	s_cmpk_gt_u32 s16, 0xff
	s_cbranch_scc1 .LBB0_892
	s_barrier
